# bundle on v64: loop-edge rotation in all four GEMM K-loops + attention counted waits + prologue cos/sin load batching
# baseline (speedup 1.0000x reference)
; #define PG8_STAGE(bufoff, gbase, voff) do { _Pragma("unroll") for (int _i = 0; _i < 2; ++_i) \
;         __builtin_amdgcn_global_load_lds((const unsigned*)((const char*)(gbase) + (voff)[_i]), (PG8_LAS unsigned*)(lds + (bufoff) + ldsw + _i * 8192), 16, 0, 0); } while (0)
; #define PG8_STAGEA(bufoff, gbase, voff) do { _Pragma("unroll") for (int _i = 0; _i < 2; ++_i) \
;         __builtin_amdgcn_global_load_lds((const unsigned*)((const char*)(gbase) + (voff)[_i]), (PG8_LAS unsigned*)(lds + (bufoff) + ldsw + _i * 8192), 16, 0, A_AUX); } while (0)
; #define PG8_LDA(dst, b, h) do { _Pragma("unroll") for (int m = 0; m < 4; ++m) _Pragma("unroll") for (int k = 0; k < 2; ++k) dst[m][k] = *(const PG8_LAS bf16x8*)(lds + PG8_SA(b, h) + aoff + m * 2048 + k * 1024); } while (0)
; #define PG8_LDB(dst, b, h) do { _Pragma("unroll") for (int n = 0; n < 2; ++n) _Pragma("unroll") for (int k = 0; k < 2; ++k) dst[n][k] = *(const PG8_LAS bf16x8*)(lds + PG8_SB(b, h) + boff + n * 2048 + k * 1024); } while (0)
; #define PG8_WAIT_V(n) asm volatile("s_waitcnt vmcnt(" #n ")" ::: "memory")
; #define PG8_WAIT_L(n) asm volatile("s_waitcnt lgkmcnt(" #n ")" ::: "memory")
; #define PG8_BAR __builtin_amdgcn_s_barrier()
;     ...
;         const bool has_next = S.next(ui + 1, nxt);
;         const char* nA = has_next ? (const char*)g.A + (size_t)nxt.pm * tstep : cA; const char* nB = has_next ? (const char*)g.Bt + (size_t)nxt.pn * tstep : cB;
;         for (int t = 0; t < nt; t += 2) {
;             const bool last = (t == nt - 2);
;             const char* a1 = cA + (size_t)(t + 1) * kstep;
;             const char* a2 = last ? nA : cA + (size_t)(t + 2) * kstep; const char* b2 = last ? nB : cB + (size_t)(t + 2) * kstep;
;             const char* a3 = a2 + kstep; const char* b3 = b2 + kstep;
;             if (last && has_next) S.a_ready(nxt);
;             if constexpr (SP2) {
;             PG8_LDB(B0, 0, 0); PG8_LDB(B1, 0, 1); PG8_SCHED; PG8_LDA(At, 0, 0); PG8_STAGEA(PG8_SA(1, 1), a1 + hstep, voffA);
;             PG8_WAIT_V(8); PG8_WAIT_L(0); PG8_BAR; PG8_MMA(0, 0, At, B0); PG8_MMA(0, 1, At, B1); PG8_BAR; PG8_SCHED;
;             PG8_LDA(At, 0, 1); PG8_STAGE(PG8_SB(0, 0), b2, voffB); PG8_STAGE(PG8_SB(0, 1), b2 + hstep, voffB); PG8_STAGEA(PG8_SA(0, 0), a2, voffA);
;             PG8_WAIT_V(8); PG8_WAIT_L(0); PG8_BAR; PG8_MMA(1, 0, At, B0); PG8_MMA(1, 1, At, B1); PG8_BAR; PG8_SCHED;
.LBB0_185:
	s_ashr_i32 s53, s52, 31
	s_lshl_b64 s[16:17], s[52:53], 19
	s_add_u32 s54, s97, s16
	s_addc_u32 s55, s29, s17
	s_and_b64 s[16:17], s[38:39], exec
	s_cselect_b32 s16, s55, s1
	s_cselect_b32 s17, s54, s0
	s_ashr_i32 s51, s50, 31
	s_lshl_b64 s[42:43], s[50:51], 19
	v_readlane_b32 s51, v246, 9
	s_add_u32 s56, s51, s42
	v_readlane_b32 s42, v246, 6
	s_addc_u32 s57, s42, s43
	s_and_b64 s[42:43], s[38:39], exec
	s_cselect_b32 s51, s57, s41
	s_cselect_b32 s53, s56, s40
	s_add_u32 s0, s0, 0x40080
	s_addc_u32 s1, s1, 0
	s_add_u32 s58, s40, 0x100
	s_addc_u32 s59, s41, 0
	s_mov_b32 vcc_lo, -2
	s_add_u32 s40, s0, 0xfffc0080
	s_addc_u32 s41, s1, -1
	s_add_i32 s70, 0, 0x10000
	s_cmp_eq_u32 vcc_lo, 12
	s_cselect_b32 s43, s16, s41
	s_cselect_b32 s42, s17, s40
	s_cselect_b32 s41, s51, s59
	s_cselect_b32 s40, s53, s58
	s_add_i32 vcc_hi, 0, 0x14000
	v_add_u32_e32 v94, s70, v201
	v_add_u32_e32 v158, vcc_hi, v201
	ds_read_b128 v[74:77], v94
	ds_read_b128 v[78:81], v94 offset:1024
	ds_read_b128 v[90:93], v94 offset:2048
	ds_read_b128 v[94:97], v94 offset:3072
	ds_read_b128 v[146:149], v158
	ds_read_b128 v[150:153], v158 offset:1024
	ds_read_b128 v[154:157], v158 offset:2048
	ds_read_b128 v[158:161], v158 offset:3072
	v_lshl_add_u64 v[190:191], s[0:1], 0, v[182:183]
	s_add_i32 m0, s61, 0xc000
	ds_read_b128 v[186:189], v203
	ds_read_b128 v[208:211], v203 offset:1024
	ds_read_b128 v[212:215], v203 offset:2048
	ds_read_b128 v[216:219], v203 offset:3072
	ds_read_b128 v[220:223], v203 offset:4096
	ds_read_b128 v[224:227], v203 offset:5120
	ds_read_b128 v[228:231], v203 offset:6144
	ds_read_b128 v[232:235], v203 offset:7168
	global_load_lds_dwordx4 v[190:191], off
	v_lshl_add_u64 v[190:191], s[0:1], 0, v[184:185]
	s_add_i32 m0, s61, 0xe000
	s_nop 0
	global_load_lds_dwordx4 v[190:191], off
	s_waitcnt vmcnt(8)
	s_waitcnt lgkmcnt(0)
	s_barrier
	s_setprio 1
	s_waitcnt lgkmcnt(0)
	v_mfma_f32_16x16x32_bf16 v[142:145], v[74:77], v[186:189], 0
	v_mfma_f32_16x16x32_bf16 v[138:141], v[90:93], v[186:189], 0
	v_mfma_f32_16x16x32_bf16 v[126:129], v[74:77], v[212:215], 0
	v_mfma_f32_16x16x32_bf16 v[122:125], v[90:93], v[212:215], 0
	v_mfma_f32_16x16x32_bf16 v[110:113], v[74:77], v[220:223], 0
	v_mfma_f32_16x16x32_bf16 v[106:109], v[90:93], v[220:223], 0
	v_mfma_f32_16x16x32_bf16 v[86:89], v[74:77], v[228:231], 0
	v_mfma_f32_16x16x32_bf16 v[82:85], v[90:93], v[228:231], 0
	v_mfma_f32_16x16x32_bf16 v[142:145], v[78:81], v[208:211], v[142:145]
	v_mfma_f32_16x16x32_bf16 v[138:141], v[94:97], v[208:211], v[138:141]
	v_mfma_f32_16x16x32_bf16 v[126:129], v[78:81], v[216:219], v[126:129]
	v_mfma_f32_16x16x32_bf16 v[122:125], v[94:97], v[216:219], v[122:125]
	v_mfma_f32_16x16x32_bf16 v[110:113], v[78:81], v[224:227], v[110:113]
	v_mfma_f32_16x16x32_bf16 v[106:109], v[94:97], v[224:227], v[106:109]
	v_mfma_f32_16x16x32_bf16 v[86:89], v[78:81], v[232:235], v[86:89]
	v_mfma_f32_16x16x32_bf16 v[82:85], v[94:97], v[232:235], v[82:85]
	s_setprio 0
	s_setprio 1
	v_mfma_f32_16x16x32_bf16 v[134:137], v[146:149], v[186:189], 0
	v_mfma_f32_16x16x32_bf16 v[130:133], v[154:157], v[186:189], 0
	v_mfma_f32_16x16x32_bf16 v[118:121], v[146:149], v[212:215], 0
	v_mfma_f32_16x16x32_bf16 v[114:117], v[154:157], v[212:215], 0
	v_mfma_f32_16x16x32_bf16 v[102:105], v[146:149], v[220:223], 0
	v_mfma_f32_16x16x32_bf16 v[98:101], v[154:157], v[220:223], 0
	v_mfma_f32_16x16x32_bf16 v[70:73], v[146:149], v[228:231], 0
	v_mfma_f32_16x16x32_bf16 v[66:69], v[154:157], v[228:231], 0
	v_mfma_f32_16x16x32_bf16 v[134:137], v[150:153], v[208:211], v[134:137]
	v_mfma_f32_16x16x32_bf16 v[130:133], v[158:161], v[208:211], v[130:133]
	v_mfma_f32_16x16x32_bf16 v[118:121], v[150:153], v[216:219], v[118:121]
	v_mfma_f32_16x16x32_bf16 v[114:117], v[158:161], v[216:219], v[114:117]
	v_mfma_f32_16x16x32_bf16 v[102:105], v[150:153], v[224:227], v[102:105]
	v_mfma_f32_16x16x32_bf16 v[98:101], v[158:161], v[224:227], v[98:101]
	v_mfma_f32_16x16x32_bf16 v[70:73], v[150:153], v[232:235], v[70:73]
	v_mfma_f32_16x16x32_bf16 v[66:69], v[158:161], v[232:235], v[66:69]
	s_setprio 0
	s_barrier
	s_add_i32 s70, s70, s60
	v_lshl_add_u64 v[190:191], s[40:41], 0, v[0:1]
	s_mov_b32 m0, s70
	ds_read_b128 v[186:189], v203 offset:16384
	ds_read_b128 v[208:211], v203 offset:17408
	ds_read_b128 v[212:215], v203 offset:18432
	ds_read_b128 v[216:219], v203 offset:19456
	ds_read_b128 v[220:223], v203 offset:20480
	ds_read_b128 v[224:227], v203 offset:21504
	ds_read_b128 v[228:231], v203 offset:22528
	ds_read_b128 v[232:235], v203 offset:23552
	global_load_lds_dwordx4 v[190:191], off
	s_add_i32 m0, s70, 0x2000
	s_add_u32 s70, s40, 0x40000
	v_lshl_add_u64 v[236:237], s[40:41], 0, v[174:175]
	s_addc_u32 s71, s41, 0
	s_add_i32 vcc_hi, vcc_hi, s60
	global_load_lds_dwordx4 v[236:237], off
	v_lshl_add_u64 v[238:239], s[70:71], 0, v[0:1]
	s_mov_b32 m0, vcc_hi
	v_lshl_add_u64 v[240:241], s[42:43], 0, v[176:177]
	global_load_lds_dwordx4 v[238:239], off
	v_lshl_add_u64 v[238:239], s[70:71], 0, v[174:175]
	s_add_i32 m0, vcc_hi, 0x2000
	s_nop 0
	global_load_lds_dwordx4 v[238:239], off
	v_lshl_add_u64 v[238:239], s[42:43], 0, v[178:179]
	s_mov_b32 m0, s61
	s_nop 0
	global_load_lds_dwordx4 v[238:239], off
	s_mov_b32 m0, s62
	s_nop 0
	global_load_lds_dwordx4 v[240:241], off
	s_waitcnt vmcnt(8)
	s_waitcnt lgkmcnt(0)
	s_barrier
; #define PG8_STAGEA(bufoff, gbase, voff) do { _Pragma("unroll") for (int _i = 0; _i < 2; ++_i) \
;         __builtin_amdgcn_global_load_lds((const unsigned*)((const char*)(gbase) + (voff)[_i]), (PG8_LAS unsigned*)(lds + (bufoff) + ldsw + _i * 8192), 16, 0, A_AUX); } while (0)
; #define PG8_LDA(dst, b, h) do { _Pragma("unroll") for (int m = 0; m < 4; ++m) _Pragma("unroll") for (int k = 0; k < 2; ++k) dst[m][k] = *(const PG8_LAS bf16x8*)(lds + PG8_SA(b, h) + aoff + m * 2048 + k * 1024); } while (0)
; #define PG8_LDB(dst, b, h) do { _Pragma("unroll") for (int n = 0; n < 2; ++n) _Pragma("unroll") for (int k = 0; k < 2; ++k) dst[n][k] = *(const PG8_LAS bf16x8*)(lds + PG8_SB(b, h) + boff + n * 2048 + k * 1024); } while (0)
; #define PG8_MMA(ai, bj, At, Bt) do { __builtin_amdgcn_s_setprio(1); _Pragma("unroll") for (int m = 0; m < 4; ++m) _Pragma("unroll") for (int n = 0; n < 2; ++n) _Pragma("unroll") for (int k = 0; k < 2; ++k) \
;         acc[ai][bj][m][n] = __builtin_amdgcn_mfma_f32_16x16x32_bf16(Bt[n][k], At[m][k], acc[ai][bj][m][n], 0, 0, 0); __builtin_amdgcn_s_setprio(0); } while (0)
; #define PG8_WAIT_V(n) asm volatile("s_waitcnt vmcnt(" #n ")" ::: "memory")
; #define PG8_WAIT_L(n) asm volatile("s_waitcnt lgkmcnt(" #n ")" ::: "memory")
; #define PG8_BAR __builtin_amdgcn_s_barrier()
; #define PG8_SCHED __builtin_amdgcn_sched_barrier(0)
;     ...
;             PG8_WAIT_V(8); PG8_WAIT_L(0); PG8_BAR; PG8_MMA(1, 0, At, B0); PG8_MMA(1, 1, At, B1); PG8_BAR; PG8_SCHED;
;             PG8_LDB(B0, 1, 0); PG8_LDB(B1, 1, 1); PG8_SCHED; PG8_LDA(At, 1, 0); PG8_STAGEA(PG8_SA(0, 1), a2 + hstep, voffA);
;             PG8_WAIT_V(8); PG8_WAIT_L(0); PG8_BAR; PG8_MMA(0, 0, At, B0); PG8_MMA(0, 1, At, B1); PG8_BAR; PG8_SCHED;
	s_setprio 1
	s_waitcnt lgkmcnt(0)
	v_mfma_f32_16x16x32_bf16 v[62:65], v[74:77], v[186:189], 0
	v_mfma_f32_16x16x32_bf16 v[58:61], v[90:93], v[186:189], 0
	v_mfma_f32_16x16x32_bf16 v[46:49], v[74:77], v[212:215], 0
	v_mfma_f32_16x16x32_bf16 v[42:45], v[90:93], v[212:215], 0
	v_mfma_f32_16x16x32_bf16 v[30:33], v[74:77], v[220:223], 0
	v_mfma_f32_16x16x32_bf16 v[26:29], v[90:93], v[220:223], 0
	v_mfma_f32_16x16x32_bf16 v[14:17], v[74:77], v[228:231], 0
	v_mfma_f32_16x16x32_bf16 v[10:13], v[90:93], v[228:231], 0
	v_mfma_f32_16x16x32_bf16 v[62:65], v[78:81], v[208:211], v[62:65]
	v_mfma_f32_16x16x32_bf16 v[58:61], v[94:97], v[208:211], v[58:61]
	v_mfma_f32_16x16x32_bf16 v[46:49], v[78:81], v[216:219], v[46:49]
	v_mfma_f32_16x16x32_bf16 v[42:45], v[94:97], v[216:219], v[42:45]
	v_mfma_f32_16x16x32_bf16 v[30:33], v[78:81], v[224:227], v[30:33]
	v_mfma_f32_16x16x32_bf16 v[26:29], v[94:97], v[224:227], v[26:29]
	v_mfma_f32_16x16x32_bf16 v[14:17], v[78:81], v[232:235], v[14:17]
	v_mfma_f32_16x16x32_bf16 v[10:13], v[94:97], v[232:235], v[10:13]
	s_setprio 0
	s_setprio 1
	v_mfma_f32_16x16x32_bf16 v[54:57], v[146:149], v[186:189], 0
	v_mfma_f32_16x16x32_bf16 v[50:53], v[154:157], v[186:189], 0
	v_mfma_f32_16x16x32_bf16 v[38:41], v[146:149], v[212:215], 0
	v_mfma_f32_16x16x32_bf16 v[34:37], v[154:157], v[212:215], 0
	v_mfma_f32_16x16x32_bf16 v[22:25], v[146:149], v[220:223], 0
	v_mfma_f32_16x16x32_bf16 v[18:21], v[154:157], v[220:223], 0
	v_mfma_f32_16x16x32_bf16 v[6:9], v[146:149], v[228:231], 0
	v_mfma_f32_16x16x32_bf16 v[2:5], v[154:157], v[228:231], 0
	v_mfma_f32_16x16x32_bf16 v[54:57], v[150:153], v[208:211], v[54:57]
	v_mfma_f32_16x16x32_bf16 v[50:53], v[158:161], v[208:211], v[50:53]
	v_mfma_f32_16x16x32_bf16 v[38:41], v[150:153], v[216:219], v[38:41]
	v_mfma_f32_16x16x32_bf16 v[34:37], v[158:161], v[216:219], v[34:37]
	v_mfma_f32_16x16x32_bf16 v[22:25], v[150:153], v[224:227], v[22:25]
	v_mfma_f32_16x16x32_bf16 v[18:21], v[158:161], v[224:227], v[18:21]
	v_mfma_f32_16x16x32_bf16 v[6:9], v[150:153], v[232:235], v[6:9]
	v_mfma_f32_16x16x32_bf16 v[2:5], v[158:161], v[232:235], v[2:5]
	s_setprio 0
	s_barrier
	s_add_i32 s70, 0, 0x18000
	s_add_i32 s71, 0, 0x1c000
	v_add_u32_e32 v94, s70, v201
	v_add_u32_e32 v158, s71, v201
	ds_read_b128 v[74:77], v94
	ds_read_b128 v[78:81], v94 offset:1024
	ds_read_b128 v[90:93], v94 offset:2048
	ds_read_b128 v[94:97], v94 offset:3072
	ds_read_b128 v[146:149], v158
	ds_read_b128 v[150:153], v158 offset:1024
	ds_read_b128 v[154:157], v158 offset:2048
	ds_read_b128 v[158:161], v158 offset:3072
	s_add_u32 s42, s42, 0x40000
	s_addc_u32 s43, s43, 0
	s_mov_b32 m0, s63
	v_lshl_add_u64 v[242:243], s[42:43], 0, v[178:179]
	ds_read_b128 v[186:189], v203 offset:32768
	ds_read_b128 v[208:211], v203 offset:33792
	ds_read_b128 v[212:215], v203 offset:34816
	ds_read_b128 v[216:219], v203 offset:35840
	ds_read_b128 v[220:223], v203 offset:36864
	ds_read_b128 v[224:227], v203 offset:37888
	ds_read_b128 v[228:231], v203 offset:38912
	ds_read_b128 v[232:235], v203 offset:39936
	global_load_lds_dwordx4 v[242:243], off
	v_lshl_add_u64 v[242:243], s[42:43], 0, v[176:177]
	s_mov_b32 m0, s64
	s_nop 0
	global_load_lds_dwordx4 v[242:243], off
	s_waitcnt vmcnt(8)
	s_waitcnt lgkmcnt(0)
	s_barrier
	s_setprio 1
	s_waitcnt lgkmcnt(0)
	v_mfma_f32_16x16x32_bf16 v[142:145], v[74:77], v[186:189], v[142:145]
	v_mfma_f32_16x16x32_bf16 v[138:141], v[90:93], v[186:189], v[138:141]
	v_mfma_f32_16x16x32_bf16 v[126:129], v[74:77], v[212:215], v[126:129]
	v_mfma_f32_16x16x32_bf16 v[122:125], v[90:93], v[212:215], v[122:125]
	v_mfma_f32_16x16x32_bf16 v[110:113], v[74:77], v[220:223], v[110:113]
	v_mfma_f32_16x16x32_bf16 v[106:109], v[90:93], v[220:223], v[106:109]
	v_mfma_f32_16x16x32_bf16 v[86:89], v[74:77], v[228:231], v[86:89]
	v_mfma_f32_16x16x32_bf16 v[82:85], v[90:93], v[228:231], v[82:85]
	v_mfma_f32_16x16x32_bf16 v[142:145], v[78:81], v[208:211], v[142:145]
	v_mfma_f32_16x16x32_bf16 v[138:141], v[94:97], v[208:211], v[138:141]
	v_mfma_f32_16x16x32_bf16 v[126:129], v[78:81], v[216:219], v[126:129]
	v_mfma_f32_16x16x32_bf16 v[122:125], v[94:97], v[216:219], v[122:125]
	v_mfma_f32_16x16x32_bf16 v[110:113], v[78:81], v[224:227], v[110:113]
	v_mfma_f32_16x16x32_bf16 v[106:109], v[94:97], v[224:227], v[106:109]
	v_mfma_f32_16x16x32_bf16 v[86:89], v[78:81], v[232:235], v[86:89]
	v_mfma_f32_16x16x32_bf16 v[82:85], v[94:97], v[232:235], v[82:85]
	s_setprio 0
	s_setprio 1
	v_mfma_f32_16x16x32_bf16 v[134:137], v[146:149], v[186:189], v[134:137]
	v_mfma_f32_16x16x32_bf16 v[130:133], v[154:157], v[186:189], v[130:133]
	v_mfma_f32_16x16x32_bf16 v[118:121], v[146:149], v[212:215], v[118:121]
	v_mfma_f32_16x16x32_bf16 v[114:117], v[154:157], v[212:215], v[114:117]
	v_mfma_f32_16x16x32_bf16 v[102:105], v[146:149], v[220:223], v[102:105]
	v_mfma_f32_16x16x32_bf16 v[98:101], v[154:157], v[220:223], v[98:101]
	v_mfma_f32_16x16x32_bf16 v[70:73], v[146:149], v[228:231], v[70:73]
	v_mfma_f32_16x16x32_bf16 v[66:69], v[154:157], v[228:231], v[66:69]
	v_mfma_f32_16x16x32_bf16 v[134:137], v[150:153], v[208:211], v[134:137]
	v_mfma_f32_16x16x32_bf16 v[130:133], v[158:161], v[208:211], v[130:133]
	v_mfma_f32_16x16x32_bf16 v[118:121], v[150:153], v[216:219], v[118:121]
	v_mfma_f32_16x16x32_bf16 v[114:117], v[158:161], v[216:219], v[114:117]
	v_mfma_f32_16x16x32_bf16 v[102:105], v[150:153], v[224:227], v[102:105]
	v_mfma_f32_16x16x32_bf16 v[98:101], v[158:161], v[224:227], v[98:101]
	v_mfma_f32_16x16x32_bf16 v[70:73], v[150:153], v[232:235], v[70:73]
	v_mfma_f32_16x16x32_bf16 v[66:69], v[158:161], v[232:235], v[66:69]
	s_setprio 0
	s_barrier
; #define PG8_STAGE(bufoff, gbase, voff) do { _Pragma("unroll") for (int _i = 0; _i < 2; ++_i) \
;         __builtin_amdgcn_global_load_lds((const unsigned*)((const char*)(gbase) + (voff)[_i]), (PG8_LAS unsigned*)(lds + (bufoff) + ldsw + _i * 8192), 16, 0, 0); } while (0)
; #define PG8_STAGEA(bufoff, gbase, voff) do { _Pragma("unroll") for (int _i = 0; _i < 2; ++_i) \
;         __builtin_amdgcn_global_load_lds((const unsigned*)((const char*)(gbase) + (voff)[_i]), (PG8_LAS unsigned*)(lds + (bufoff) + ldsw + _i * 8192), 16, 0, A_AUX); } while (0)
; #define PG8_LDA(dst, b, h) do { _Pragma("unroll") for (int m = 0; m < 4; ++m) _Pragma("unroll") for (int k = 0; k < 2; ++k) dst[m][k] = *(const PG8_LAS bf16x8*)(lds + PG8_SA(b, h) + aoff + m * 2048 + k * 1024); } while (0)
; #define PG8_MMA(ai, bj, At, Bt) do { __builtin_amdgcn_s_setprio(1); _Pragma("unroll") for (int m = 0; m < 4; ++m) _Pragma("unroll") for (int n = 0; n < 2; ++n) _Pragma("unroll") for (int k = 0; k < 2; ++k) \
;         acc[ai][bj][m][n] = __builtin_amdgcn_mfma_f32_16x16x32_bf16(Bt[n][k], At[m][k], acc[ai][bj][m][n], 0, 0, 0); __builtin_amdgcn_s_setprio(0); } while (0)
; #define PG8_WAIT_V(n) asm volatile("s_waitcnt vmcnt(" #n ")" ::: "memory")
; #define PG8_WAIT_L(n) asm volatile("s_waitcnt lgkmcnt(" #n ")" ::: "memory")
; #define PG8_BAR __builtin_amdgcn_s_barrier()
; #define PG8_SCHED __builtin_amdgcn_sched_barrier(0)
;     ...
;         for (int t = 0; t < nt; t += 2) {
;     ...
;             PG8_LDA(At, 1, 1); PG8_STAGE(PG8_SB(1, 0), b3, voffB); PG8_STAGE(PG8_SB(1, 1), b3 + hstep, voffB); PG8_STAGEA(PG8_SA(1, 0), a3, voffA);
;             PG8_WAIT_V(8); PG8_WAIT_L(0); PG8_BAR; PG8_MMA(1, 0, At, B0); PG8_MMA(1, 1, At, B1); PG8_BAR; PG8_SCHED;
	s_add_i32 s42, s70, s60
	v_lshl_add_u64 v[190:191], v[190:191], 0, s[8:9]
	s_mov_b32 m0, s42
	ds_read_b128 v[186:189], v203 offset:49152
	ds_read_b128 v[208:211], v203 offset:50176
	ds_read_b128 v[212:215], v203 offset:51200
	ds_read_b128 v[216:219], v203 offset:52224
	ds_read_b128 v[220:223], v203 offset:53248
	ds_read_b128 v[224:227], v203 offset:54272
	ds_read_b128 v[228:231], v203 offset:55296
	ds_read_b128 v[232:235], v203 offset:56320
	global_load_lds_dwordx4 v[190:191], off
	s_add_i32 m0, s42, 0x2000
	s_add_u32 s40, s40, 0x40080
	v_lshl_add_u64 v[190:191], v[236:237], 0, s[8:9]
	s_addc_u32 s41, s41, 0
	s_add_i32 s42, s71, s60
	global_load_lds_dwordx4 v[190:191], off
	v_lshl_add_u64 v[190:191], s[40:41], 0, v[0:1]
	s_mov_b32 m0, s42
	s_nop 0
	global_load_lds_dwordx4 v[190:191], off
	v_lshl_add_u64 v[190:191], s[40:41], 0, v[174:175]
	s_add_i32 m0, s42, 0x2000
	s_nop 0
	global_load_lds_dwordx4 v[190:191], off
	v_lshl_add_u64 v[190:191], v[238:239], 0, s[8:9]
	s_mov_b32 m0, s72
	s_nop 0
	global_load_lds_dwordx4 v[190:191], off
	v_lshl_add_u64 v[190:191], v[240:241], 0, s[8:9]
	s_mov_b32 m0, s73
	s_nop 0
	global_load_lds_dwordx4 v[190:191], off
	s_waitcnt vmcnt(8)
	s_waitcnt lgkmcnt(0)
	s_barrier
	s_setprio 1
	s_waitcnt lgkmcnt(0)
	v_mfma_f32_16x16x32_bf16 v[62:65], v[74:77], v[186:189], v[62:65]
	v_mfma_f32_16x16x32_bf16 v[58:61], v[90:93], v[186:189], v[58:61]
	v_mfma_f32_16x16x32_bf16 v[46:49], v[74:77], v[212:215], v[46:49]
	v_mfma_f32_16x16x32_bf16 v[42:45], v[90:93], v[212:215], v[42:45]
	v_mfma_f32_16x16x32_bf16 v[30:33], v[74:77], v[220:223], v[30:33]
	v_mfma_f32_16x16x32_bf16 v[26:29], v[90:93], v[220:223], v[26:29]
	v_mfma_f32_16x16x32_bf16 v[14:17], v[74:77], v[228:231], v[14:17]
	v_mfma_f32_16x16x32_bf16 v[10:13], v[90:93], v[228:231], v[10:13]
	v_mfma_f32_16x16x32_bf16 v[62:65], v[78:81], v[208:211], v[62:65]
	v_mfma_f32_16x16x32_bf16 v[58:61], v[94:97], v[208:211], v[58:61]
	v_mfma_f32_16x16x32_bf16 v[46:49], v[78:81], v[216:219], v[46:49]
	v_mfma_f32_16x16x32_bf16 v[42:45], v[94:97], v[216:219], v[42:45]
	v_mfma_f32_16x16x32_bf16 v[30:33], v[78:81], v[224:227], v[30:33]
	v_mfma_f32_16x16x32_bf16 v[26:29], v[94:97], v[224:227], v[26:29]
	v_mfma_f32_16x16x32_bf16 v[14:17], v[78:81], v[232:235], v[14:17]
	v_mfma_f32_16x16x32_bf16 v[10:13], v[94:97], v[232:235], v[10:13]
	s_setprio 0
	s_setprio 1
	v_mfma_f32_16x16x32_bf16 v[54:57], v[146:149], v[186:189], v[54:57]
	v_mfma_f32_16x16x32_bf16 v[50:53], v[154:157], v[186:189], v[50:53]
	v_mfma_f32_16x16x32_bf16 v[38:41], v[146:149], v[212:215], v[38:41]
	v_mfma_f32_16x16x32_bf16 v[34:37], v[154:157], v[212:215], v[34:37]
	s_add_i32 vcc_lo, vcc_lo, 2
	s_add_u32 s0, s0, 0x100
	s_addc_u32 s1, s1, 0
	s_add_u32 s58, s58, 0x100
	s_addc_u32 s59, s59, 0
	s_add_u32 s40, s0, 0xfffc0080
	s_addc_u32 s41, s1, -1
	s_add_i32 s70, 0, 0x10000
	s_cmp_eq_u32 vcc_lo, 12
	s_cselect_b32 s43, s16, s41
	s_cselect_b32 s42, s17, s40
	s_cselect_b32 s41, s51, s59
	s_cselect_b32 s40, s53, s58
	s_add_i32 vcc_hi, 0, 0x14000
	v_mfma_f32_16x16x32_bf16 v[22:25], v[146:149], v[220:223], v[22:25]
	v_mfma_f32_16x16x32_bf16 v[18:21], v[154:157], v[220:223], v[18:21]
	v_mfma_f32_16x16x32_bf16 v[6:9], v[146:149], v[228:231], v[6:9]
	v_mfma_f32_16x16x32_bf16 v[2:5], v[154:157], v[228:231], v[2:5]
	v_mfma_f32_16x16x32_bf16 v[54:57], v[150:153], v[208:211], v[54:57]
	v_mfma_f32_16x16x32_bf16 v[50:53], v[158:161], v[208:211], v[50:53]
	v_mfma_f32_16x16x32_bf16 v[38:41], v[150:153], v[216:219], v[38:41]
	v_mfma_f32_16x16x32_bf16 v[34:37], v[158:161], v[216:219], v[34:37]
	v_mfma_f32_16x16x32_bf16 v[22:25], v[150:153], v[224:227], v[22:25]
	v_mfma_f32_16x16x32_bf16 v[18:21], v[158:161], v[224:227], v[18:21]
	v_mfma_f32_16x16x32_bf16 v[6:9], v[150:153], v[232:235], v[6:9]
	v_mfma_f32_16x16x32_bf16 v[2:5], v[158:161], v[232:235], v[2:5]
	s_setprio 0
	s_barrier
.LBB0_186:
	v_add_u32_e32 v94, s70, v201
	v_add_u32_e32 v158, vcc_hi, v201
	ds_read_b128 v[74:77], v94
	ds_read_b128 v[78:81], v94 offset:1024
	ds_read_b128 v[90:93], v94 offset:2048
	ds_read_b128 v[94:97], v94 offset:3072
	ds_read_b128 v[146:149], v158
	ds_read_b128 v[150:153], v158 offset:1024
	ds_read_b128 v[154:157], v158 offset:2048
	ds_read_b128 v[158:161], v158 offset:3072
	v_lshl_add_u64 v[190:191], s[0:1], 0, v[182:183]
	s_add_i32 m0, s61, 0xc000
	ds_read_b128 v[186:189], v203
	ds_read_b128 v[208:211], v203 offset:1024
	ds_read_b128 v[212:215], v203 offset:2048
	ds_read_b128 v[216:219], v203 offset:3072
	ds_read_b128 v[220:223], v203 offset:4096
	ds_read_b128 v[224:227], v203 offset:5120
	ds_read_b128 v[228:231], v203 offset:6144
	ds_read_b128 v[232:235], v203 offset:7168
	global_load_lds_dwordx4 v[190:191], off
	v_lshl_add_u64 v[190:191], s[0:1], 0, v[184:185]
	s_add_i32 m0, s61, 0xe000
	s_nop 0
	global_load_lds_dwordx4 v[190:191], off
	s_waitcnt vmcnt(8)
	s_waitcnt lgkmcnt(0)
	s_barrier
; #define PG8_STAGE(bufoff, gbase, voff) do { _Pragma("unroll") for (int _i = 0; _i < 2; ++_i) \
;         __builtin_amdgcn_global_load_lds((const unsigned*)((const char*)(gbase) + (voff)[_i]), (PG8_LAS unsigned*)(lds + (bufoff) + ldsw + _i * 8192), 16, 0, 0); } while (0)
; #define PG8_STAGEA(bufoff, gbase, voff) do { _Pragma("unroll") for (int _i = 0; _i < 2; ++_i) \
;         __builtin_amdgcn_global_load_lds((const unsigned*)((const char*)(gbase) + (voff)[_i]), (PG8_LAS unsigned*)(lds + (bufoff) + ldsw + _i * 8192), 16, 0, A_AUX); } while (0)
; #define PG8_LDA(dst, b, h) do { _Pragma("unroll") for (int m = 0; m < 4; ++m) _Pragma("unroll") for (int k = 0; k < 2; ++k) dst[m][k] = *(const PG8_LAS bf16x8*)(lds + PG8_SA(b, h) + aoff + m * 2048 + k * 1024); } while (0)
; #define PG8_MMA(ai, bj, At, Bt) do { __builtin_amdgcn_s_setprio(1); _Pragma("unroll") for (int m = 0; m < 4; ++m) _Pragma("unroll") for (int n = 0; n < 2; ++n) _Pragma("unroll") for (int k = 0; k < 2; ++k) \
;         acc[ai][bj][m][n] = __builtin_amdgcn_mfma_f32_16x16x32_bf16(Bt[n][k], At[m][k], acc[ai][bj][m][n], 0, 0, 0); __builtin_amdgcn_s_setprio(0); } while (0)
; #define PG8_WAIT_V(n) asm volatile("s_waitcnt vmcnt(" #n ")" ::: "memory")
; #define PG8_WAIT_L(n) asm volatile("s_waitcnt lgkmcnt(" #n ")" ::: "memory")
; #define PG8_BAR __builtin_amdgcn_s_barrier()
; #define PG8_SCHED __builtin_amdgcn_sched_barrier(0)
;     ...
;             PG8_WAIT_V(8); PG8_WAIT_L(0); PG8_BAR; PG8_MMA(0, 0, At, B0); PG8_MMA(0, 1, At, B1); PG8_BAR; PG8_SCHED;
;             PG8_LDA(At, 0, 1); PG8_STAGE(PG8_SB(0, 0), b2, voffB); PG8_STAGE(PG8_SB(0, 1), b2 + hstep, voffB); PG8_STAGEA(PG8_SA(0, 0), a2, voffA);
;             PG8_WAIT_V(8); PG8_WAIT_L(0); PG8_BAR; PG8_MMA(1, 0, At, B0); PG8_MMA(1, 1, At, B1); PG8_BAR; PG8_SCHED;
	s_setprio 1
	s_waitcnt lgkmcnt(0)
	v_mfma_f32_16x16x32_bf16 v[142:145], v[74:77], v[186:189], v[142:145]
	v_mfma_f32_16x16x32_bf16 v[138:141], v[90:93], v[186:189], v[138:141]
	v_mfma_f32_16x16x32_bf16 v[126:129], v[74:77], v[212:215], v[126:129]
	v_mfma_f32_16x16x32_bf16 v[122:125], v[90:93], v[212:215], v[122:125]
	v_mfma_f32_16x16x32_bf16 v[110:113], v[74:77], v[220:223], v[110:113]
	v_mfma_f32_16x16x32_bf16 v[106:109], v[90:93], v[220:223], v[106:109]
	v_mfma_f32_16x16x32_bf16 v[86:89], v[74:77], v[228:231], v[86:89]
	v_mfma_f32_16x16x32_bf16 v[82:85], v[90:93], v[228:231], v[82:85]
	v_mfma_f32_16x16x32_bf16 v[142:145], v[78:81], v[208:211], v[142:145]
	v_mfma_f32_16x16x32_bf16 v[138:141], v[94:97], v[208:211], v[138:141]
	v_mfma_f32_16x16x32_bf16 v[126:129], v[78:81], v[216:219], v[126:129]
	v_mfma_f32_16x16x32_bf16 v[122:125], v[94:97], v[216:219], v[122:125]
	v_mfma_f32_16x16x32_bf16 v[110:113], v[78:81], v[224:227], v[110:113]
	v_mfma_f32_16x16x32_bf16 v[106:109], v[94:97], v[224:227], v[106:109]
	v_mfma_f32_16x16x32_bf16 v[86:89], v[78:81], v[232:235], v[86:89]
	v_mfma_f32_16x16x32_bf16 v[82:85], v[94:97], v[232:235], v[82:85]
	s_setprio 0
	s_setprio 1
	v_mfma_f32_16x16x32_bf16 v[134:137], v[146:149], v[186:189], v[134:137]
	v_mfma_f32_16x16x32_bf16 v[130:133], v[154:157], v[186:189], v[130:133]
	v_mfma_f32_16x16x32_bf16 v[118:121], v[146:149], v[212:215], v[118:121]
	v_mfma_f32_16x16x32_bf16 v[114:117], v[154:157], v[212:215], v[114:117]
	v_mfma_f32_16x16x32_bf16 v[102:105], v[146:149], v[220:223], v[102:105]
	v_mfma_f32_16x16x32_bf16 v[98:101], v[154:157], v[220:223], v[98:101]
	v_mfma_f32_16x16x32_bf16 v[70:73], v[146:149], v[228:231], v[70:73]
	v_mfma_f32_16x16x32_bf16 v[66:69], v[154:157], v[228:231], v[66:69]
	v_mfma_f32_16x16x32_bf16 v[134:137], v[150:153], v[208:211], v[134:137]
	v_mfma_f32_16x16x32_bf16 v[130:133], v[158:161], v[208:211], v[130:133]
	v_mfma_f32_16x16x32_bf16 v[118:121], v[150:153], v[216:219], v[118:121]
	v_mfma_f32_16x16x32_bf16 v[114:117], v[158:161], v[216:219], v[114:117]
	v_mfma_f32_16x16x32_bf16 v[102:105], v[150:153], v[224:227], v[102:105]
	v_mfma_f32_16x16x32_bf16 v[98:101], v[158:161], v[224:227], v[98:101]
	v_mfma_f32_16x16x32_bf16 v[70:73], v[150:153], v[232:235], v[70:73]
	v_mfma_f32_16x16x32_bf16 v[66:69], v[158:161], v[232:235], v[66:69]
	s_setprio 0
	s_barrier
	s_add_i32 s70, s70, s60
	v_lshl_add_u64 v[190:191], s[40:41], 0, v[0:1]
	s_mov_b32 m0, s70
	ds_read_b128 v[186:189], v203 offset:16384
	ds_read_b128 v[208:211], v203 offset:17408
	ds_read_b128 v[212:215], v203 offset:18432
	ds_read_b128 v[216:219], v203 offset:19456
	ds_read_b128 v[220:223], v203 offset:20480
	ds_read_b128 v[224:227], v203 offset:21504
	ds_read_b128 v[228:231], v203 offset:22528
	ds_read_b128 v[232:235], v203 offset:23552
	global_load_lds_dwordx4 v[190:191], off
	s_add_i32 m0, s70, 0x2000
	s_add_u32 s70, s40, 0x40000
	v_lshl_add_u64 v[236:237], s[40:41], 0, v[174:175]
	s_addc_u32 s71, s41, 0
	s_add_i32 vcc_hi, vcc_hi, s60
	global_load_lds_dwordx4 v[236:237], off
	v_lshl_add_u64 v[238:239], s[70:71], 0, v[0:1]
	s_mov_b32 m0, vcc_hi
	v_lshl_add_u64 v[240:241], s[42:43], 0, v[176:177]
	global_load_lds_dwordx4 v[238:239], off
	v_lshl_add_u64 v[238:239], s[70:71], 0, v[174:175]
	s_add_i32 m0, vcc_hi, 0x2000
	s_nop 0
	global_load_lds_dwordx4 v[238:239], off
	v_lshl_add_u64 v[238:239], s[42:43], 0, v[178:179]
	s_mov_b32 m0, s61
	s_nop 0
	global_load_lds_dwordx4 v[238:239], off
	s_mov_b32 m0, s62
	s_nop 0
	global_load_lds_dwordx4 v[240:241], off
	s_waitcnt vmcnt(8)
	s_waitcnt lgkmcnt(0)
	s_barrier
	s_setprio 1
	s_waitcnt lgkmcnt(0)
	v_mfma_f32_16x16x32_bf16 v[62:65], v[74:77], v[186:189], v[62:65]
	v_mfma_f32_16x16x32_bf16 v[58:61], v[90:93], v[186:189], v[58:61]
	v_mfma_f32_16x16x32_bf16 v[46:49], v[74:77], v[212:215], v[46:49]
	v_mfma_f32_16x16x32_bf16 v[42:45], v[90:93], v[212:215], v[42:45]
	v_mfma_f32_16x16x32_bf16 v[30:33], v[74:77], v[220:223], v[30:33]
	v_mfma_f32_16x16x32_bf16 v[26:29], v[90:93], v[220:223], v[26:29]
	v_mfma_f32_16x16x32_bf16 v[14:17], v[74:77], v[228:231], v[14:17]
	v_mfma_f32_16x16x32_bf16 v[10:13], v[90:93], v[228:231], v[10:13]
	v_mfma_f32_16x16x32_bf16 v[62:65], v[78:81], v[208:211], v[62:65]
	v_mfma_f32_16x16x32_bf16 v[58:61], v[94:97], v[208:211], v[58:61]
	v_mfma_f32_16x16x32_bf16 v[46:49], v[78:81], v[216:219], v[46:49]
	v_mfma_f32_16x16x32_bf16 v[42:45], v[94:97], v[216:219], v[42:45]
	v_mfma_f32_16x16x32_bf16 v[30:33], v[78:81], v[224:227], v[30:33]
	v_mfma_f32_16x16x32_bf16 v[26:29], v[94:97], v[224:227], v[26:29]
	v_mfma_f32_16x16x32_bf16 v[14:17], v[78:81], v[232:235], v[14:17]
	v_mfma_f32_16x16x32_bf16 v[10:13], v[94:97], v[232:235], v[10:13]
	s_setprio 0
	s_setprio 1
	v_mfma_f32_16x16x32_bf16 v[54:57], v[146:149], v[186:189], v[54:57]
	v_mfma_f32_16x16x32_bf16 v[50:53], v[154:157], v[186:189], v[50:53]
	v_mfma_f32_16x16x32_bf16 v[38:41], v[146:149], v[212:215], v[38:41]
	v_mfma_f32_16x16x32_bf16 v[34:37], v[154:157], v[212:215], v[34:37]
	v_mfma_f32_16x16x32_bf16 v[22:25], v[146:149], v[220:223], v[22:25]
	v_mfma_f32_16x16x32_bf16 v[18:21], v[154:157], v[220:223], v[18:21]
	v_mfma_f32_16x16x32_bf16 v[6:9], v[146:149], v[228:231], v[6:9]
	v_mfma_f32_16x16x32_bf16 v[2:5], v[154:157], v[228:231], v[2:5]
	v_mfma_f32_16x16x32_bf16 v[54:57], v[150:153], v[208:211], v[54:57]
	v_mfma_f32_16x16x32_bf16 v[50:53], v[158:161], v[208:211], v[50:53]
	v_mfma_f32_16x16x32_bf16 v[38:41], v[150:153], v[216:219], v[38:41]
	v_mfma_f32_16x16x32_bf16 v[34:37], v[158:161], v[216:219], v[34:37]
	v_mfma_f32_16x16x32_bf16 v[22:25], v[150:153], v[224:227], v[22:25]
	v_mfma_f32_16x16x32_bf16 v[18:21], v[158:161], v[224:227], v[18:21]
	v_mfma_f32_16x16x32_bf16 v[6:9], v[150:153], v[232:235], v[6:9]
	v_mfma_f32_16x16x32_bf16 v[2:5], v[158:161], v[232:235], v[2:5]
	s_setprio 0
	s_barrier
; #define PG8_STAGEA(bufoff, gbase, voff) do { _Pragma("unroll") for (int _i = 0; _i < 2; ++_i) \
;         __builtin_amdgcn_global_load_lds((const unsigned*)((const char*)(gbase) + (voff)[_i]), (PG8_LAS unsigned*)(lds + (bufoff) + ldsw + _i * 8192), 16, 0, A_AUX); } while (0)
; #define PG8_LDA(dst, b, h) do { _Pragma("unroll") for (int m = 0; m < 4; ++m) _Pragma("unroll") for (int k = 0; k < 2; ++k) dst[m][k] = *(const PG8_LAS bf16x8*)(lds + PG8_SA(b, h) + aoff + m * 2048 + k * 1024); } while (0)
; #define PG8_LDB(dst, b, h) do { _Pragma("unroll") for (int n = 0; n < 2; ++n) _Pragma("unroll") for (int k = 0; k < 2; ++k) dst[n][k] = *(const PG8_LAS bf16x8*)(lds + PG8_SB(b, h) + boff + n * 2048 + k * 1024); } while (0)
; #define PG8_MMA(ai, bj, At, Bt) do { __builtin_amdgcn_s_setprio(1); _Pragma("unroll") for (int m = 0; m < 4; ++m) _Pragma("unroll") for (int n = 0; n < 2; ++n) _Pragma("unroll") for (int k = 0; k < 2; ++k) \
;         acc[ai][bj][m][n] = __builtin_amdgcn_mfma_f32_16x16x32_bf16(Bt[n][k], At[m][k], acc[ai][bj][m][n], 0, 0, 0); __builtin_amdgcn_s_setprio(0); } while (0)
; #define PG8_WAIT_V(n) asm volatile("s_waitcnt vmcnt(" #n ")" ::: "memory")
; #define PG8_WAIT_L(n) asm volatile("s_waitcnt lgkmcnt(" #n ")" ::: "memory")
; #define PG8_BAR __builtin_amdgcn_s_barrier()
; #define PG8_SCHED __builtin_amdgcn_sched_barrier(0)
;     ...
;             PG8_LDB(B0, 1, 0); PG8_LDB(B1, 1, 1); PG8_SCHED; PG8_LDA(At, 1, 0); PG8_STAGEA(PG8_SA(0, 1), a2 + hstep, voffA);
;             PG8_WAIT_V(8); PG8_WAIT_L(0); PG8_BAR; PG8_MMA(0, 0, At, B0); PG8_MMA(0, 1, At, B1); PG8_BAR; PG8_SCHED;
	s_add_i32 s70, 0, 0x18000
	s_add_i32 s71, 0, 0x1c000
	v_add_u32_e32 v94, s70, v201
	v_add_u32_e32 v158, s71, v201
	ds_read_b128 v[74:77], v94
	ds_read_b128 v[78:81], v94 offset:1024
	ds_read_b128 v[90:93], v94 offset:2048
	ds_read_b128 v[94:97], v94 offset:3072
	ds_read_b128 v[146:149], v158
	ds_read_b128 v[150:153], v158 offset:1024
	ds_read_b128 v[154:157], v158 offset:2048
	ds_read_b128 v[158:161], v158 offset:3072
	s_add_u32 s42, s42, 0x40000
	s_addc_u32 s43, s43, 0
	s_mov_b32 m0, s63
	v_lshl_add_u64 v[242:243], s[42:43], 0, v[178:179]
	ds_read_b128 v[186:189], v203 offset:32768
	ds_read_b128 v[208:211], v203 offset:33792
	ds_read_b128 v[212:215], v203 offset:34816
	ds_read_b128 v[216:219], v203 offset:35840
	ds_read_b128 v[220:223], v203 offset:36864
	ds_read_b128 v[224:227], v203 offset:37888
	ds_read_b128 v[228:231], v203 offset:38912
	ds_read_b128 v[232:235], v203 offset:39936
	global_load_lds_dwordx4 v[242:243], off
	v_lshl_add_u64 v[242:243], s[42:43], 0, v[176:177]
	s_mov_b32 m0, s64
	s_nop 0
	global_load_lds_dwordx4 v[242:243], off
	s_waitcnt vmcnt(8)
	s_waitcnt lgkmcnt(0)
	s_barrier
	s_setprio 1
	s_waitcnt lgkmcnt(0)
	v_mfma_f32_16x16x32_bf16 v[142:145], v[74:77], v[186:189], v[142:145]
	v_mfma_f32_16x16x32_bf16 v[138:141], v[90:93], v[186:189], v[138:141]
	v_mfma_f32_16x16x32_bf16 v[126:129], v[74:77], v[212:215], v[126:129]
	v_mfma_f32_16x16x32_bf16 v[122:125], v[90:93], v[212:215], v[122:125]
	v_mfma_f32_16x16x32_bf16 v[110:113], v[74:77], v[220:223], v[110:113]
	v_mfma_f32_16x16x32_bf16 v[106:109], v[90:93], v[220:223], v[106:109]
	v_mfma_f32_16x16x32_bf16 v[86:89], v[74:77], v[228:231], v[86:89]
	v_mfma_f32_16x16x32_bf16 v[82:85], v[90:93], v[228:231], v[82:85]
	v_mfma_f32_16x16x32_bf16 v[142:145], v[78:81], v[208:211], v[142:145]
	v_mfma_f32_16x16x32_bf16 v[138:141], v[94:97], v[208:211], v[138:141]
	v_mfma_f32_16x16x32_bf16 v[126:129], v[78:81], v[216:219], v[126:129]
	v_mfma_f32_16x16x32_bf16 v[122:125], v[94:97], v[216:219], v[122:125]
	v_mfma_f32_16x16x32_bf16 v[110:113], v[78:81], v[224:227], v[110:113]
	v_mfma_f32_16x16x32_bf16 v[106:109], v[94:97], v[224:227], v[106:109]
	v_mfma_f32_16x16x32_bf16 v[86:89], v[78:81], v[232:235], v[86:89]
	v_mfma_f32_16x16x32_bf16 v[82:85], v[94:97], v[232:235], v[82:85]
	s_setprio 0
	s_setprio 1
	v_mfma_f32_16x16x32_bf16 v[134:137], v[146:149], v[186:189], v[134:137]
	v_mfma_f32_16x16x32_bf16 v[130:133], v[154:157], v[186:189], v[130:133]
	v_mfma_f32_16x16x32_bf16 v[118:121], v[146:149], v[212:215], v[118:121]
	v_mfma_f32_16x16x32_bf16 v[114:117], v[154:157], v[212:215], v[114:117]
	v_mfma_f32_16x16x32_bf16 v[102:105], v[146:149], v[220:223], v[102:105]
	v_mfma_f32_16x16x32_bf16 v[98:101], v[154:157], v[220:223], v[98:101]
	v_mfma_f32_16x16x32_bf16 v[70:73], v[146:149], v[228:231], v[70:73]
	v_mfma_f32_16x16x32_bf16 v[66:69], v[154:157], v[228:231], v[66:69]
	v_mfma_f32_16x16x32_bf16 v[134:137], v[150:153], v[208:211], v[134:137]
	v_mfma_f32_16x16x32_bf16 v[130:133], v[158:161], v[208:211], v[130:133]
	v_mfma_f32_16x16x32_bf16 v[118:121], v[150:153], v[216:219], v[118:121]
	v_mfma_f32_16x16x32_bf16 v[114:117], v[158:161], v[216:219], v[114:117]
	v_mfma_f32_16x16x32_bf16 v[102:105], v[150:153], v[224:227], v[102:105]
	v_mfma_f32_16x16x32_bf16 v[98:101], v[158:161], v[224:227], v[98:101]
	v_mfma_f32_16x16x32_bf16 v[70:73], v[150:153], v[232:235], v[70:73]
	v_mfma_f32_16x16x32_bf16 v[66:69], v[158:161], v[232:235], v[66:69]
	s_setprio 0
	s_barrier
; #define PG8_STAGE(bufoff, gbase, voff) do { _Pragma("unroll") for (int _i = 0; _i < 2; ++_i) \
;         __builtin_amdgcn_global_load_lds((const unsigned*)((const char*)(gbase) + (voff)[_i]), (PG8_LAS unsigned*)(lds + (bufoff) + ldsw + _i * 8192), 16, 0, 0); } while (0)
; #define PG8_STAGEA(bufoff, gbase, voff) do { _Pragma("unroll") for (int _i = 0; _i < 2; ++_i) \
;         __builtin_amdgcn_global_load_lds((const unsigned*)((const char*)(gbase) + (voff)[_i]), (PG8_LAS unsigned*)(lds + (bufoff) + ldsw + _i * 8192), 16, 0, A_AUX); } while (0)
; #define PG8_LDA(dst, b, h) do { _Pragma("unroll") for (int m = 0; m < 4; ++m) _Pragma("unroll") for (int k = 0; k < 2; ++k) dst[m][k] = *(const PG8_LAS bf16x8*)(lds + PG8_SA(b, h) + aoff + m * 2048 + k * 1024); } while (0)
; #define PG8_MMA(ai, bj, At, Bt) do { __builtin_amdgcn_s_setprio(1); _Pragma("unroll") for (int m = 0; m < 4; ++m) _Pragma("unroll") for (int n = 0; n < 2; ++n) _Pragma("unroll") for (int k = 0; k < 2; ++k) \
;         acc[ai][bj][m][n] = __builtin_amdgcn_mfma_f32_16x16x32_bf16(Bt[n][k], At[m][k], acc[ai][bj][m][n], 0, 0, 0); __builtin_amdgcn_s_setprio(0); } while (0)
; #define PG8_WAIT_V(n) asm volatile("s_waitcnt vmcnt(" #n ")" ::: "memory")
; #define PG8_WAIT_L(n) asm volatile("s_waitcnt lgkmcnt(" #n ")" ::: "memory")
; #define PG8_BAR __builtin_amdgcn_s_barrier()
; #define PG8_SCHED __builtin_amdgcn_sched_barrier(0)
;     ...
;             PG8_LDA(At, 1, 1); PG8_STAGE(PG8_SB(1, 0), b3, voffB); PG8_STAGE(PG8_SB(1, 1), b3 + hstep, voffB); PG8_STAGEA(PG8_SA(1, 0), a3, voffA);
;             PG8_WAIT_V(8); PG8_WAIT_L(0); PG8_BAR; PG8_MMA(1, 0, At, B0); PG8_MMA(1, 1, At, B1); PG8_BAR; PG8_SCHED;
;     ...
;         if constexpr (ALIGN_EPI) { if (wr == 0) PG8_BAR; }
	s_add_i32 s42, s70, s60
	v_lshl_add_u64 v[190:191], v[190:191], 0, s[8:9]
	s_mov_b32 m0, s42
	ds_read_b128 v[186:189], v203 offset:49152
	ds_read_b128 v[208:211], v203 offset:50176
	ds_read_b128 v[212:215], v203 offset:51200
	ds_read_b128 v[216:219], v203 offset:52224
	ds_read_b128 v[220:223], v203 offset:53248
	ds_read_b128 v[224:227], v203 offset:54272
	ds_read_b128 v[228:231], v203 offset:55296
	ds_read_b128 v[232:235], v203 offset:56320
	global_load_lds_dwordx4 v[190:191], off
	s_add_i32 m0, s42, 0x2000
	s_add_u32 s40, s40, 0x40080
	v_lshl_add_u64 v[190:191], v[236:237], 0, s[8:9]
	s_addc_u32 s41, s41, 0
	s_add_i32 s42, s71, s60
	global_load_lds_dwordx4 v[190:191], off
	v_lshl_add_u64 v[190:191], s[40:41], 0, v[0:1]
	s_mov_b32 m0, s42
	s_nop 0
	global_load_lds_dwordx4 v[190:191], off
	v_lshl_add_u64 v[190:191], s[40:41], 0, v[174:175]
	s_add_i32 m0, s42, 0x2000
	s_nop 0
	global_load_lds_dwordx4 v[190:191], off
	v_lshl_add_u64 v[190:191], v[238:239], 0, s[8:9]
	s_mov_b32 m0, s72
	s_nop 0
	global_load_lds_dwordx4 v[190:191], off
	v_lshl_add_u64 v[190:191], v[240:241], 0, s[8:9]
	s_mov_b32 m0, s73
	s_nop 0
	global_load_lds_dwordx4 v[190:191], off
	s_waitcnt vmcnt(8)
	s_waitcnt lgkmcnt(0)
	s_barrier
	s_setprio 1
	s_waitcnt lgkmcnt(0)
	v_mfma_f32_16x16x32_bf16 v[62:65], v[74:77], v[186:189], v[62:65]
	v_mfma_f32_16x16x32_bf16 v[58:61], v[90:93], v[186:189], v[58:61]
	v_mfma_f32_16x16x32_bf16 v[46:49], v[74:77], v[212:215], v[46:49]
	v_mfma_f32_16x16x32_bf16 v[42:45], v[90:93], v[212:215], v[42:45]
	v_mfma_f32_16x16x32_bf16 v[30:33], v[74:77], v[220:223], v[30:33]
	v_mfma_f32_16x16x32_bf16 v[26:29], v[90:93], v[220:223], v[26:29]
	v_mfma_f32_16x16x32_bf16 v[14:17], v[74:77], v[228:231], v[14:17]
	v_mfma_f32_16x16x32_bf16 v[10:13], v[90:93], v[228:231], v[10:13]
	v_mfma_f32_16x16x32_bf16 v[62:65], v[78:81], v[208:211], v[62:65]
	v_mfma_f32_16x16x32_bf16 v[58:61], v[94:97], v[208:211], v[58:61]
	v_mfma_f32_16x16x32_bf16 v[46:49], v[78:81], v[216:219], v[46:49]
	v_mfma_f32_16x16x32_bf16 v[42:45], v[94:97], v[216:219], v[42:45]
	v_mfma_f32_16x16x32_bf16 v[30:33], v[78:81], v[224:227], v[30:33]
	v_mfma_f32_16x16x32_bf16 v[26:29], v[94:97], v[224:227], v[26:29]
	v_mfma_f32_16x16x32_bf16 v[14:17], v[78:81], v[232:235], v[14:17]
	v_mfma_f32_16x16x32_bf16 v[10:13], v[94:97], v[232:235], v[10:13]
	s_setprio 0
	s_setprio 1
	v_mfma_f32_16x16x32_bf16 v[54:57], v[146:149], v[186:189], v[54:57]
	v_mfma_f32_16x16x32_bf16 v[50:53], v[154:157], v[186:189], v[50:53]
	v_mfma_f32_16x16x32_bf16 v[38:41], v[146:149], v[212:215], v[38:41]
	v_mfma_f32_16x16x32_bf16 v[34:37], v[154:157], v[212:215], v[34:37]
	s_add_i32 vcc_lo, vcc_lo, 2
	s_add_u32 s0, s0, 0x100
	s_addc_u32 s1, s1, 0
	s_add_u32 s58, s58, 0x100
	s_addc_u32 s59, s59, 0
	s_add_u32 s40, s0, 0xfffc0080
	s_addc_u32 s41, s1, -1
	s_add_i32 s70, 0, 0x10000
	s_cmp_eq_u32 vcc_lo, 12
	s_cselect_b32 s43, s16, s41
	s_cselect_b32 s42, s17, s40
	s_cselect_b32 s41, s51, s59
	s_cselect_b32 s40, s53, s58
	s_add_i32 vcc_hi, 0, 0x14000
	v_mfma_f32_16x16x32_bf16 v[22:25], v[146:149], v[220:223], v[22:25]
	v_mfma_f32_16x16x32_bf16 v[18:21], v[154:157], v[220:223], v[18:21]
	v_mfma_f32_16x16x32_bf16 v[6:9], v[146:149], v[228:231], v[6:9]
	v_mfma_f32_16x16x32_bf16 v[2:5], v[154:157], v[228:231], v[2:5]
	v_mfma_f32_16x16x32_bf16 v[54:57], v[150:153], v[208:211], v[54:57]
	v_mfma_f32_16x16x32_bf16 v[50:53], v[158:161], v[208:211], v[50:53]
	v_mfma_f32_16x16x32_bf16 v[38:41], v[150:153], v[216:219], v[38:41]
	v_mfma_f32_16x16x32_bf16 v[34:37], v[158:161], v[216:219], v[34:37]
	v_mfma_f32_16x16x32_bf16 v[22:25], v[150:153], v[224:227], v[22:25]
	v_mfma_f32_16x16x32_bf16 v[18:21], v[158:161], v[224:227], v[18:21]
	v_mfma_f32_16x16x32_bf16 v[6:9], v[150:153], v[232:235], v[6:9]
	v_mfma_f32_16x16x32_bf16 v[2:5], v[158:161], v[232:235], v[2:5]
	s_setprio 0
	s_barrier
	s_cmp_gt_u32 vcc_lo, 13
	s_cbranch_scc0 .LBB0_186
	s_and_b64 vcc, exec, s[46:47]
	s_cbranch_vccz .LBB0_189
	s_barrier

; #define PG8_STAGE(bufoff, gbase, voff) do { _Pragma("unroll") for (int _i = 0; _i < 2; ++_i) \
;         __builtin_amdgcn_global_load_lds((const unsigned*)((const char*)(gbase) + (voff)[_i]), (PG8_LAS unsigned*)(lds + (bufoff) + ldsw + _i * 8192), 16, 0, 0); } while (0)
; #define PG8_STAGEA(bufoff, gbase, voff) do { _Pragma("unroll") for (int _i = 0; _i < 2; ++_i) \
;         __builtin_amdgcn_global_load_lds((const unsigned*)((const char*)(gbase) + (voff)[_i]), (PG8_LAS unsigned*)(lds + (bufoff) + ldsw + _i * 8192), 16, 0, A_AUX); } while (0)
; #define PG8_LDA(dst, b, h) do { _Pragma("unroll") for (int m = 0; m < 4; ++m) _Pragma("unroll") for (int k = 0; k < 2; ++k) dst[m][k] = *(const PG8_LAS bf16x8*)(lds + PG8_SA(b, h) + aoff + m * 2048 + k * 1024); } while (0)
; #define PG8_LDB(dst, b, h) do { _Pragma("unroll") for (int n = 0; n < 2; ++n) _Pragma("unroll") for (int k = 0; k < 2; ++k) dst[n][k] = *(const PG8_LAS bf16x8*)(lds + PG8_SB(b, h) + boff + n * 2048 + k * 1024); } while (0)
; #define PG8_WAIT_V(n) asm volatile("s_waitcnt vmcnt(" #n ")" ::: "memory")
; #define PG8_WAIT_L(n) asm volatile("s_waitcnt lgkmcnt(" #n ")" ::: "memory")
; #define PG8_BAR __builtin_amdgcn_s_barrier()
;     ...
;         const bool has_next = S.next(ui + 1, nxt);
;         const char* nA = has_next ? (const char*)g.A + (size_t)nxt.pm * tstep : cA; const char* nB = has_next ? (const char*)g.Bt + (size_t)nxt.pn * tstep : cB;
;         for (int t = 0; t < nt; t += 2) {
;             const bool last = (t == nt - 2);
;             const char* a1 = cA + (size_t)(t + 1) * kstep;
;             const char* a2 = last ? nA : cA + (size_t)(t + 2) * kstep; const char* b2 = last ? nB : cB + (size_t)(t + 2) * kstep;
;             const char* a3 = a2 + kstep; const char* b3 = b2 + kstep;
;             if (last && has_next) S.a_ready(nxt);
;             if constexpr (SP2) {
;             PG8_LDB(B0, 0, 0); PG8_LDB(B1, 0, 1); PG8_SCHED; PG8_LDA(At, 0, 0); PG8_STAGEA(PG8_SA(1, 1), a1 + hstep, voffA);
;             PG8_WAIT_V(8); PG8_WAIT_L(0); PG8_BAR; PG8_MMA(0, 0, At, B0); PG8_MMA(0, 1, At, B1); PG8_BAR; PG8_SCHED;
;             PG8_LDA(At, 0, 1); PG8_STAGE(PG8_SB(0, 0), b2, voffB); PG8_STAGE(PG8_SB(0, 1), b2 + hstep, voffB); PG8_STAGEA(PG8_SA(0, 0), a2, voffA);
;             PG8_WAIT_V(8); PG8_WAIT_L(0); PG8_BAR; PG8_MMA(1, 0, At, B0); PG8_MMA(1, 1, At, B1); PG8_BAR; PG8_SCHED;
.LBB0_442:
	s_ashr_i32 s43, s42, 31
	s_lshl_b64 s[16:17], s[42:43], 19
	s_add_u32 s44, s24, s16
	s_addc_u32 s45, s25, s17
	s_and_b64 s[16:17], s[38:39], exec
	s_cselect_b32 s16, s45, s49
	s_cselect_b32 s17, s44, s48
	s_ashr_i32 s41, s40, 31
	s_lshl_b64 s[46:47], s[40:41], 19
	s_add_u32 s46, s23, s46
	s_addc_u32 s47, s54, s47
	s_and_b64 s[52:53], s[38:39], exec
	s_cselect_b32 s41, s47, s51
	s_cselect_b32 s43, s46, s50
	s_add_u32 s48, s48, 0x40080
	s_addc_u32 s49, s49, 0
	s_add_u32 s65, s50, 0x100
	s_addc_u32 s72, s51, 0
	s_mov_b32 s73, -2
	s_add_u32 s50, s48, 0xfffc0080
	s_addc_u32 s51, s49, -1
	s_add_i32 s70, 0, 0x10000
	s_cmp_eq_u32 s73, 12
	s_cselect_b32 s53, s16, s51
	s_cselect_b32 s52, s17, s50
	s_cselect_b32 s51, s41, s72
	s_cselect_b32 s50, s43, s65
	s_add_i32 s76, 0, 0x14000
	v_add_u32_e32 v140, s70, v143
	ds_read_b128 v[146:149], v140
	ds_read_b128 v[150:153], v140 offset:1024
	ds_read_b128 v[154:157], v140 offset:2048
	ds_read_b128 v[158:161], v140 offset:3072
	v_add_u32_e32 v140, s76, v143
	ds_read_b128 v[174:177], v140
	ds_read_b128 v[178:181], v140 offset:1024
	ds_read_b128 v[182:185], v140 offset:2048
	ds_read_b128 v[186:189], v140 offset:3072
	v_lshl_add_u64 v[140:141], s[48:49], 0, v[136:137]
	s_add_i32 m0, s56, 0xc000
	ds_read_b128 v[200:203], v145
	ds_read_b128 v[208:211], v145 offset:1024
	ds_read_b128 v[212:215], v145 offset:2048
	ds_read_b128 v[216:219], v145 offset:3072
	ds_read_b128 v[220:223], v145 offset:4096
	ds_read_b128 v[224:227], v145 offset:5120
	ds_read_b128 v[228:231], v145 offset:6144
	ds_read_b128 v[232:235], v145 offset:7168
	global_load_lds_dwordx4 v[140:141], off
	v_lshl_add_u64 v[140:141], s[48:49], 0, v[138:139]
	s_add_i32 m0, s56, 0xe000
	s_nop 0
	global_load_lds_dwordx4 v[140:141], off
	s_waitcnt vmcnt(8)
	s_waitcnt lgkmcnt(0)
	s_barrier
	s_setprio 1
	s_waitcnt lgkmcnt(0)
	v_mfma_f32_16x16x32_bf16 v[126:129], v[146:149], v[200:203], 0
	v_mfma_f32_16x16x32_bf16 v[122:125], v[154:157], v[200:203], 0
	v_mfma_f32_16x16x32_bf16 v[114:117], v[146:149], v[212:215], 0
	v_mfma_f32_16x16x32_bf16 v[106:109], v[154:157], v[212:215], 0
	v_mfma_f32_16x16x32_bf16 v[98:101], v[146:149], v[220:223], 0
	v_mfma_f32_16x16x32_bf16 v[90:93], v[154:157], v[220:223], 0
	v_mfma_f32_16x16x32_bf16 v[82:85], v[146:149], v[228:231], 0
	v_mfma_f32_16x16x32_bf16 v[74:77], v[154:157], v[228:231], 0
	v_mfma_f32_16x16x32_bf16 v[126:129], v[150:153], v[208:211], v[126:129]
	v_mfma_f32_16x16x32_bf16 v[122:125], v[158:161], v[208:211], v[122:125]
	v_mfma_f32_16x16x32_bf16 v[114:117], v[150:153], v[216:219], v[114:117]
	v_mfma_f32_16x16x32_bf16 v[106:109], v[158:161], v[216:219], v[106:109]
	v_mfma_f32_16x16x32_bf16 v[98:101], v[150:153], v[224:227], v[98:101]
	v_mfma_f32_16x16x32_bf16 v[90:93], v[158:161], v[224:227], v[90:93]
	v_mfma_f32_16x16x32_bf16 v[82:85], v[150:153], v[232:235], v[82:85]
	v_mfma_f32_16x16x32_bf16 v[74:77], v[158:161], v[232:235], v[74:77]
	s_setprio 0
	s_setprio 1
	v_mfma_f32_16x16x32_bf16 v[118:121], v[174:177], v[200:203], 0
	v_mfma_f32_16x16x32_bf16 v[110:113], v[182:185], v[200:203], 0
	v_mfma_f32_16x16x32_bf16 v[102:105], v[174:177], v[212:215], 0
	v_mfma_f32_16x16x32_bf16 v[94:97], v[182:185], v[212:215], 0
	v_mfma_f32_16x16x32_bf16 v[86:89], v[174:177], v[220:223], 0
	v_mfma_f32_16x16x32_bf16 v[78:81], v[182:185], v[220:223], 0
	v_mfma_f32_16x16x32_bf16 v[70:73], v[174:177], v[228:231], 0
	v_mfma_f32_16x16x32_bf16 v[66:69], v[182:185], v[228:231], 0
	v_mfma_f32_16x16x32_bf16 v[118:121], v[178:181], v[208:211], v[118:121]
	v_mfma_f32_16x16x32_bf16 v[110:113], v[186:189], v[208:211], v[110:113]
	v_mfma_f32_16x16x32_bf16 v[102:105], v[178:181], v[216:219], v[102:105]
	v_mfma_f32_16x16x32_bf16 v[94:97], v[186:189], v[216:219], v[94:97]
	v_mfma_f32_16x16x32_bf16 v[86:89], v[178:181], v[224:227], v[86:89]
	v_mfma_f32_16x16x32_bf16 v[78:81], v[186:189], v[224:227], v[78:81]
	v_mfma_f32_16x16x32_bf16 v[70:73], v[178:181], v[232:235], v[70:73]
	v_mfma_f32_16x16x32_bf16 v[66:69], v[186:189], v[232:235], v[66:69]
	s_setprio 0
	s_barrier
	s_add_i32 s70, s70, s55
	v_lshl_add_u64 v[140:141], s[50:51], 0, v[0:1]
	s_mov_b32 m0, s70
	ds_read_b128 v[200:203], v145 offset:16384
	ds_read_b128 v[208:211], v145 offset:17408
	ds_read_b128 v[212:215], v145 offset:18432
	ds_read_b128 v[216:219], v145 offset:19456
	ds_read_b128 v[220:223], v145 offset:20480
	ds_read_b128 v[224:227], v145 offset:21504
	ds_read_b128 v[228:231], v145 offset:22528
	ds_read_b128 v[232:235], v145 offset:23552
	global_load_lds_dwordx4 v[140:141], off
	s_add_i32 m0, s70, 0x2000
	s_add_u32 s70, s50, 0x40000
	v_lshl_add_u64 v[190:191], s[50:51], 0, v[130:131]
	s_addc_u32 s71, s51, 0
	s_add_i32 s76, s76, s55
	global_load_lds_dwordx4 v[190:191], off
	v_lshl_add_u64 v[236:237], s[70:71], 0, v[0:1]
	s_mov_b32 m0, s76
	v_lshl_add_u64 v[238:239], s[52:53], 0, v[132:133]
	global_load_lds_dwordx4 v[236:237], off
	v_lshl_add_u64 v[236:237], s[70:71], 0, v[130:131]
	s_add_i32 m0, s76, 0x2000
	s_nop 0
	global_load_lds_dwordx4 v[236:237], off
	v_lshl_add_u64 v[236:237], s[52:53], 0, v[134:135]
	s_mov_b32 m0, s56
	s_nop 0
	global_load_lds_dwordx4 v[236:237], off
	s_mov_b32 m0, s57
	s_nop 0
	global_load_lds_dwordx4 v[238:239], off
	s_waitcnt vmcnt(8)
	s_waitcnt lgkmcnt(0)
	s_barrier
; #define PG8_STAGEA(bufoff, gbase, voff) do { _Pragma("unroll") for (int _i = 0; _i < 2; ++_i) \
;         __builtin_amdgcn_global_load_lds((const unsigned*)((const char*)(gbase) + (voff)[_i]), (PG8_LAS unsigned*)(lds + (bufoff) + ldsw + _i * 8192), 16, 0, A_AUX); } while (0)
; #define PG8_LDA(dst, b, h) do { _Pragma("unroll") for (int m = 0; m < 4; ++m) _Pragma("unroll") for (int k = 0; k < 2; ++k) dst[m][k] = *(const PG8_LAS bf16x8*)(lds + PG8_SA(b, h) + aoff + m * 2048 + k * 1024); } while (0)
; #define PG8_LDB(dst, b, h) do { _Pragma("unroll") for (int n = 0; n < 2; ++n) _Pragma("unroll") for (int k = 0; k < 2; ++k) dst[n][k] = *(const PG8_LAS bf16x8*)(lds + PG8_SB(b, h) + boff + n * 2048 + k * 1024); } while (0)
; #define PG8_MMA(ai, bj, At, Bt) do { __builtin_amdgcn_s_setprio(1); _Pragma("unroll") for (int m = 0; m < 4; ++m) _Pragma("unroll") for (int n = 0; n < 2; ++n) _Pragma("unroll") for (int k = 0; k < 2; ++k) \
;         acc[ai][bj][m][n] = __builtin_amdgcn_mfma_f32_16x16x32_bf16(Bt[n][k], At[m][k], acc[ai][bj][m][n], 0, 0, 0); __builtin_amdgcn_s_setprio(0); } while (0)
; #define PG8_WAIT_V(n) asm volatile("s_waitcnt vmcnt(" #n ")" ::: "memory")
; #define PG8_WAIT_L(n) asm volatile("s_waitcnt lgkmcnt(" #n ")" ::: "memory")
; #define PG8_BAR __builtin_amdgcn_s_barrier()
; #define PG8_SCHED __builtin_amdgcn_sched_barrier(0)
;     ...
;             PG8_WAIT_V(8); PG8_WAIT_L(0); PG8_BAR; PG8_MMA(1, 0, At, B0); PG8_MMA(1, 1, At, B1); PG8_BAR; PG8_SCHED;
;             PG8_LDB(B0, 1, 0); PG8_LDB(B1, 1, 1); PG8_SCHED; PG8_LDA(At, 1, 0); PG8_STAGEA(PG8_SA(0, 1), a2 + hstep, voffA);
;             PG8_WAIT_V(8); PG8_WAIT_L(0); PG8_BAR; PG8_MMA(0, 0, At, B0); PG8_MMA(0, 1, At, B1); PG8_BAR; PG8_SCHED;
	s_setprio 1
	s_waitcnt lgkmcnt(0)
	v_mfma_f32_16x16x32_bf16 v[62:65], v[146:149], v[200:203], 0
	v_mfma_f32_16x16x32_bf16 v[58:61], v[154:157], v[200:203], 0
	v_mfma_f32_16x16x32_bf16 v[50:53], v[146:149], v[212:215], 0
	v_mfma_f32_16x16x32_bf16 v[42:45], v[154:157], v[212:215], 0
	v_mfma_f32_16x16x32_bf16 v[34:37], v[146:149], v[220:223], 0
	v_mfma_f32_16x16x32_bf16 v[26:29], v[154:157], v[220:223], 0
	v_mfma_f32_16x16x32_bf16 v[18:21], v[146:149], v[228:231], 0
	v_mfma_f32_16x16x32_bf16 v[10:13], v[154:157], v[228:231], 0
	v_mfma_f32_16x16x32_bf16 v[62:65], v[150:153], v[208:211], v[62:65]
	v_mfma_f32_16x16x32_bf16 v[58:61], v[158:161], v[208:211], v[58:61]
	v_mfma_f32_16x16x32_bf16 v[50:53], v[150:153], v[216:219], v[50:53]
	v_mfma_f32_16x16x32_bf16 v[42:45], v[158:161], v[216:219], v[42:45]
	v_mfma_f32_16x16x32_bf16 v[34:37], v[150:153], v[224:227], v[34:37]
	v_mfma_f32_16x16x32_bf16 v[26:29], v[158:161], v[224:227], v[26:29]
	v_mfma_f32_16x16x32_bf16 v[18:21], v[150:153], v[232:235], v[18:21]
	v_mfma_f32_16x16x32_bf16 v[10:13], v[158:161], v[232:235], v[10:13]
	s_setprio 0
	s_setprio 1
	v_mfma_f32_16x16x32_bf16 v[54:57], v[174:177], v[200:203], 0
	v_mfma_f32_16x16x32_bf16 v[46:49], v[182:185], v[200:203], 0
	v_mfma_f32_16x16x32_bf16 v[38:41], v[174:177], v[212:215], 0
	v_mfma_f32_16x16x32_bf16 v[30:33], v[182:185], v[212:215], 0
	v_mfma_f32_16x16x32_bf16 v[22:25], v[174:177], v[220:223], 0
	v_mfma_f32_16x16x32_bf16 v[14:17], v[182:185], v[220:223], 0
	v_mfma_f32_16x16x32_bf16 v[6:9], v[174:177], v[228:231], 0
	v_mfma_f32_16x16x32_bf16 v[2:5], v[182:185], v[228:231], 0
	v_mfma_f32_16x16x32_bf16 v[54:57], v[178:181], v[208:211], v[54:57]
	v_mfma_f32_16x16x32_bf16 v[46:49], v[186:189], v[208:211], v[46:49]
	v_mfma_f32_16x16x32_bf16 v[38:41], v[178:181], v[216:219], v[38:41]
	v_mfma_f32_16x16x32_bf16 v[30:33], v[186:189], v[216:219], v[30:33]
	v_mfma_f32_16x16x32_bf16 v[22:25], v[178:181], v[224:227], v[22:25]
	v_mfma_f32_16x16x32_bf16 v[14:17], v[186:189], v[224:227], v[14:17]
	v_mfma_f32_16x16x32_bf16 v[6:9], v[178:181], v[232:235], v[6:9]
	v_mfma_f32_16x16x32_bf16 v[2:5], v[186:189], v[232:235], v[2:5]
	s_setprio 0
	s_barrier
	s_add_i32 s70, 0, 0x18000
	s_add_i32 s71, 0, 0x1c000
	v_add_u32_e32 v158, s70, v143
	v_add_u32_e32 v186, s71, v143
	ds_read_b128 v[146:149], v158
	ds_read_b128 v[150:153], v158 offset:1024
	ds_read_b128 v[154:157], v158 offset:2048
	ds_read_b128 v[158:161], v158 offset:3072
	ds_read_b128 v[174:177], v186
	ds_read_b128 v[178:181], v186 offset:1024
	ds_read_b128 v[182:185], v186 offset:2048
	ds_read_b128 v[186:189], v186 offset:3072
	s_add_u32 s52, s52, 0x40000
	s_addc_u32 s53, s53, 0
	s_mov_b32 m0, s58
	v_lshl_add_u64 v[240:241], s[52:53], 0, v[134:135]
	ds_read_b128 v[200:203], v145 offset:32768
	ds_read_b128 v[208:211], v145 offset:33792
	ds_read_b128 v[212:215], v145 offset:34816
	ds_read_b128 v[216:219], v145 offset:35840
	ds_read_b128 v[220:223], v145 offset:36864
	ds_read_b128 v[224:227], v145 offset:37888
	ds_read_b128 v[228:231], v145 offset:38912
	ds_read_b128 v[232:235], v145 offset:39936
	global_load_lds_dwordx4 v[240:241], off
	v_lshl_add_u64 v[240:241], s[52:53], 0, v[132:133]
	s_mov_b32 m0, s59
	s_nop 0
	global_load_lds_dwordx4 v[240:241], off
	s_waitcnt vmcnt(8)
	s_waitcnt lgkmcnt(0)
	s_barrier
	s_setprio 1
	s_waitcnt lgkmcnt(0)
	v_mfma_f32_16x16x32_bf16 v[126:129], v[146:149], v[200:203], v[126:129]
	v_mfma_f32_16x16x32_bf16 v[122:125], v[154:157], v[200:203], v[122:125]
	v_mfma_f32_16x16x32_bf16 v[114:117], v[146:149], v[212:215], v[114:117]
	v_mfma_f32_16x16x32_bf16 v[106:109], v[154:157], v[212:215], v[106:109]
	v_mfma_f32_16x16x32_bf16 v[98:101], v[146:149], v[220:223], v[98:101]
	v_mfma_f32_16x16x32_bf16 v[90:93], v[154:157], v[220:223], v[90:93]
	v_mfma_f32_16x16x32_bf16 v[82:85], v[146:149], v[228:231], v[82:85]
	v_mfma_f32_16x16x32_bf16 v[74:77], v[154:157], v[228:231], v[74:77]
	v_mfma_f32_16x16x32_bf16 v[126:129], v[150:153], v[208:211], v[126:129]
	v_mfma_f32_16x16x32_bf16 v[122:125], v[158:161], v[208:211], v[122:125]
	v_mfma_f32_16x16x32_bf16 v[114:117], v[150:153], v[216:219], v[114:117]
	v_mfma_f32_16x16x32_bf16 v[106:109], v[158:161], v[216:219], v[106:109]
	v_mfma_f32_16x16x32_bf16 v[98:101], v[150:153], v[224:227], v[98:101]
	v_mfma_f32_16x16x32_bf16 v[90:93], v[158:161], v[224:227], v[90:93]
	v_mfma_f32_16x16x32_bf16 v[82:85], v[150:153], v[232:235], v[82:85]
	v_mfma_f32_16x16x32_bf16 v[74:77], v[158:161], v[232:235], v[74:77]
	s_setprio 0
	s_setprio 1
	v_mfma_f32_16x16x32_bf16 v[118:121], v[174:177], v[200:203], v[118:121]
	v_mfma_f32_16x16x32_bf16 v[110:113], v[182:185], v[200:203], v[110:113]
	v_mfma_f32_16x16x32_bf16 v[102:105], v[174:177], v[212:215], v[102:105]
	v_mfma_f32_16x16x32_bf16 v[94:97], v[182:185], v[212:215], v[94:97]
	v_mfma_f32_16x16x32_bf16 v[86:89], v[174:177], v[220:223], v[86:89]
	v_mfma_f32_16x16x32_bf16 v[78:81], v[182:185], v[220:223], v[78:81]
	v_mfma_f32_16x16x32_bf16 v[70:73], v[174:177], v[228:231], v[70:73]
	v_mfma_f32_16x16x32_bf16 v[66:69], v[182:185], v[228:231], v[66:69]
	v_mfma_f32_16x16x32_bf16 v[118:121], v[178:181], v[208:211], v[118:121]
	v_mfma_f32_16x16x32_bf16 v[110:113], v[186:189], v[208:211], v[110:113]
	v_mfma_f32_16x16x32_bf16 v[102:105], v[178:181], v[216:219], v[102:105]
	v_mfma_f32_16x16x32_bf16 v[94:97], v[186:189], v[216:219], v[94:97]
	v_mfma_f32_16x16x32_bf16 v[86:89], v[178:181], v[224:227], v[86:89]
	v_mfma_f32_16x16x32_bf16 v[78:81], v[186:189], v[224:227], v[78:81]
	v_mfma_f32_16x16x32_bf16 v[70:73], v[178:181], v[232:235], v[70:73]
	v_mfma_f32_16x16x32_bf16 v[66:69], v[186:189], v[232:235], v[66:69]
	s_setprio 0
	s_barrier
; #define PG8_STAGE(bufoff, gbase, voff) do { _Pragma("unroll") for (int _i = 0; _i < 2; ++_i) \
;         __builtin_amdgcn_global_load_lds((const unsigned*)((const char*)(gbase) + (voff)[_i]), (PG8_LAS unsigned*)(lds + (bufoff) + ldsw + _i * 8192), 16, 0, 0); } while (0)
; #define PG8_STAGEA(bufoff, gbase, voff) do { _Pragma("unroll") for (int _i = 0; _i < 2; ++_i) \
;         __builtin_amdgcn_global_load_lds((const unsigned*)((const char*)(gbase) + (voff)[_i]), (PG8_LAS unsigned*)(lds + (bufoff) + ldsw + _i * 8192), 16, 0, A_AUX); } while (0)
; #define PG8_LDA(dst, b, h) do { _Pragma("unroll") for (int m = 0; m < 4; ++m) _Pragma("unroll") for (int k = 0; k < 2; ++k) dst[m][k] = *(const PG8_LAS bf16x8*)(lds + PG8_SA(b, h) + aoff + m * 2048 + k * 1024); } while (0)
; #define PG8_WAIT_V(n) asm volatile("s_waitcnt vmcnt(" #n ")" ::: "memory")
; #define PG8_BAR __builtin_amdgcn_s_barrier()
;     ...
;         for (int t = 0; t < nt; t += 2) {
;             const bool last = (t == nt - 2);
;             const char* a1 = cA + (size_t)(t + 1) * kstep;
;             const char* a2 = last ? nA : cA + (size_t)(t + 2) * kstep; const char* b2 = last ? nB : cB + (size_t)(t + 2) * kstep;
;             const char* a3 = a2 + kstep; const char* b3 = b2 + kstep;
;             if (last && has_next) S.a_ready(nxt);
;             if constexpr (SP2) {
;             PG8_LDB(B0, 0, 0); PG8_LDB(B1, 0, 1); PG8_SCHED; PG8_LDA(At, 0, 0); PG8_STAGEA(PG8_SA(1, 1), a1 + hstep, voffA);
;             PG8_WAIT_V(8); PG8_WAIT_L(0); PG8_BAR; PG8_MMA(0, 0, At, B0); PG8_MMA(0, 1, At, B1); PG8_BAR; PG8_SCHED;
;             PG8_LDA(At, 0, 1); PG8_STAGE(PG8_SB(0, 0), b2, voffB); PG8_STAGE(PG8_SB(0, 1), b2 + hstep, voffB); PG8_STAGEA(PG8_SA(0, 0), a2, voffA);
;             PG8_WAIT_V(8); PG8_WAIT_L(0); PG8_BAR; PG8_MMA(1, 0, At, B0); PG8_MMA(1, 1, At, B1); PG8_BAR; PG8_SCHED;
;             PG8_LDB(B0, 1, 0); PG8_LDB(B1, 1, 1); PG8_SCHED; PG8_LDA(At, 1, 0); PG8_STAGEA(PG8_SA(0, 1), a2 + hstep, voffA);
;             PG8_WAIT_V(8); PG8_WAIT_L(0); PG8_BAR; PG8_MMA(0, 0, At, B0); PG8_MMA(0, 1, At, B1); PG8_BAR; PG8_SCHED;
;             PG8_LDA(At, 1, 1); PG8_STAGE(PG8_SB(1, 0), b3, voffB); PG8_STAGE(PG8_SB(1, 1), b3 + hstep, voffB); PG8_STAGEA(PG8_SA(1, 0), a3, voffA);
;             PG8_WAIT_V(8); PG8_WAIT_L(0); PG8_BAR; PG8_MMA(1, 0, At, B0); PG8_MMA(1, 1, At, B1); PG8_BAR; PG8_SCHED;
	s_add_i32 s52, s70, s55
	v_lshl_add_u64 v[140:141], v[140:141], 0, s[8:9]
	s_mov_b32 m0, s52
	ds_read_b128 v[200:203], v145 offset:49152
	ds_read_b128 v[208:211], v145 offset:50176
	ds_read_b128 v[212:215], v145 offset:51200
	ds_read_b128 v[216:219], v145 offset:52224
	ds_read_b128 v[220:223], v145 offset:53248
	ds_read_b128 v[224:227], v145 offset:54272
	ds_read_b128 v[228:231], v145 offset:55296
	ds_read_b128 v[232:235], v145 offset:56320
	global_load_lds_dwordx4 v[140:141], off
	s_add_i32 m0, s52, 0x2000
	s_add_u32 s50, s50, 0x40080
	v_lshl_add_u64 v[140:141], v[190:191], 0, s[8:9]
	s_addc_u32 s51, s51, 0
	s_add_i32 s52, s71, s55
	global_load_lds_dwordx4 v[140:141], off
	v_lshl_add_u64 v[140:141], s[50:51], 0, v[0:1]
	s_mov_b32 m0, s52
	s_nop 0
	global_load_lds_dwordx4 v[140:141], off
	v_lshl_add_u64 v[140:141], s[50:51], 0, v[130:131]
	s_add_i32 m0, s52, 0x2000
	s_nop 0
	global_load_lds_dwordx4 v[140:141], off
	v_lshl_add_u64 v[140:141], v[236:237], 0, s[8:9]
	s_mov_b32 m0, s60
	s_nop 0
	global_load_lds_dwordx4 v[140:141], off
	v_lshl_add_u64 v[140:141], v[238:239], 0, s[8:9]
	s_mov_b32 m0, s61
	s_nop 0
	global_load_lds_dwordx4 v[140:141], off
	s_waitcnt vmcnt(8)
	s_waitcnt lgkmcnt(0)
	s_barrier
	s_setprio 1
	s_waitcnt lgkmcnt(0)
	v_mfma_f32_16x16x32_bf16 v[62:65], v[146:149], v[200:203], v[62:65]
	v_mfma_f32_16x16x32_bf16 v[58:61], v[154:157], v[200:203], v[58:61]
	v_mfma_f32_16x16x32_bf16 v[50:53], v[146:149], v[212:215], v[50:53]
	v_mfma_f32_16x16x32_bf16 v[42:45], v[154:157], v[212:215], v[42:45]
	v_mfma_f32_16x16x32_bf16 v[34:37], v[146:149], v[220:223], v[34:37]
	v_mfma_f32_16x16x32_bf16 v[26:29], v[154:157], v[220:223], v[26:29]
	v_mfma_f32_16x16x32_bf16 v[18:21], v[146:149], v[228:231], v[18:21]
	v_mfma_f32_16x16x32_bf16 v[10:13], v[154:157], v[228:231], v[10:13]
	v_mfma_f32_16x16x32_bf16 v[62:65], v[150:153], v[208:211], v[62:65]
	v_mfma_f32_16x16x32_bf16 v[58:61], v[158:161], v[208:211], v[58:61]
	v_mfma_f32_16x16x32_bf16 v[50:53], v[150:153], v[216:219], v[50:53]
	v_mfma_f32_16x16x32_bf16 v[42:45], v[158:161], v[216:219], v[42:45]
	v_mfma_f32_16x16x32_bf16 v[34:37], v[150:153], v[224:227], v[34:37]
	v_mfma_f32_16x16x32_bf16 v[26:29], v[158:161], v[224:227], v[26:29]
	v_mfma_f32_16x16x32_bf16 v[18:21], v[150:153], v[232:235], v[18:21]
	v_mfma_f32_16x16x32_bf16 v[10:13], v[158:161], v[232:235], v[10:13]
	s_setprio 0
	s_setprio 1
	v_mfma_f32_16x16x32_bf16 v[54:57], v[174:177], v[200:203], v[54:57]
	v_mfma_f32_16x16x32_bf16 v[46:49], v[182:185], v[200:203], v[46:49]
	v_mfma_f32_16x16x32_bf16 v[38:41], v[174:177], v[212:215], v[38:41]
	v_mfma_f32_16x16x32_bf16 v[30:33], v[182:185], v[212:215], v[30:33]
	s_add_i32 s73, s73, 2
	s_add_u32 s48, s48, 0x100
	s_addc_u32 s49, s49, 0
	s_add_u32 s65, s65, 0x100
	s_addc_u32 s72, s72, 0
	s_add_u32 s50, s48, 0xfffc0080
	s_addc_u32 s51, s49, -1
	s_add_i32 s70, 0, 0x10000
	s_cmp_eq_u32 s73, 12
	s_cselect_b32 s53, s16, s51
	s_cselect_b32 s52, s17, s50
	s_cselect_b32 s51, s41, s72
	s_cselect_b32 s50, s43, s65
	s_add_i32 s76, 0, 0x14000
	v_mfma_f32_16x16x32_bf16 v[22:25], v[174:177], v[220:223], v[22:25]
	v_mfma_f32_16x16x32_bf16 v[14:17], v[182:185], v[220:223], v[14:17]
	v_mfma_f32_16x16x32_bf16 v[6:9], v[174:177], v[228:231], v[6:9]
	v_mfma_f32_16x16x32_bf16 v[2:5], v[182:185], v[228:231], v[2:5]
	v_mfma_f32_16x16x32_bf16 v[54:57], v[178:181], v[208:211], v[54:57]
	v_mfma_f32_16x16x32_bf16 v[46:49], v[186:189], v[208:211], v[46:49]
	v_mfma_f32_16x16x32_bf16 v[38:41], v[178:181], v[216:219], v[38:41]
	v_mfma_f32_16x16x32_bf16 v[30:33], v[186:189], v[216:219], v[30:33]
	v_mfma_f32_16x16x32_bf16 v[22:25], v[178:181], v[224:227], v[22:25]
	v_mfma_f32_16x16x32_bf16 v[14:17], v[186:189], v[224:227], v[14:17]
	v_mfma_f32_16x16x32_bf16 v[6:9], v[178:181], v[232:235], v[6:9]
	v_mfma_f32_16x16x32_bf16 v[2:5], v[186:189], v[232:235], v[2:5]
	s_setprio 0
	s_barrier
.LBB0_443:
	v_add_u32_e32 v140, s70, v143
	ds_read_b128 v[146:149], v140
	ds_read_b128 v[150:153], v140 offset:1024
	ds_read_b128 v[154:157], v140 offset:2048
	ds_read_b128 v[158:161], v140 offset:3072
	v_add_u32_e32 v140, s76, v143
	ds_read_b128 v[174:177], v140
	ds_read_b128 v[178:181], v140 offset:1024
	ds_read_b128 v[182:185], v140 offset:2048
	ds_read_b128 v[186:189], v140 offset:3072
	v_lshl_add_u64 v[140:141], s[48:49], 0, v[136:137]
	s_add_i32 m0, s56, 0xc000
	ds_read_b128 v[200:203], v145
	ds_read_b128 v[208:211], v145 offset:1024
	ds_read_b128 v[212:215], v145 offset:2048
	ds_read_b128 v[216:219], v145 offset:3072
	ds_read_b128 v[220:223], v145 offset:4096
	ds_read_b128 v[224:227], v145 offset:5120
	ds_read_b128 v[228:231], v145 offset:6144
	ds_read_b128 v[232:235], v145 offset:7168
	global_load_lds_dwordx4 v[140:141], off
	v_lshl_add_u64 v[140:141], s[48:49], 0, v[138:139]
	s_add_i32 m0, s56, 0xe000
	s_nop 0
	global_load_lds_dwordx4 v[140:141], off
	s_waitcnt vmcnt(8)
	s_waitcnt lgkmcnt(0)
	s_barrier
; #define PG8_STAGE(bufoff, gbase, voff) do { _Pragma("unroll") for (int _i = 0; _i < 2; ++_i) \
;         __builtin_amdgcn_global_load_lds((const unsigned*)((const char*)(gbase) + (voff)[_i]), (PG8_LAS unsigned*)(lds + (bufoff) + ldsw + _i * 8192), 16, 0, 0); } while (0)
; #define PG8_STAGEA(bufoff, gbase, voff) do { _Pragma("unroll") for (int _i = 0; _i < 2; ++_i) \
;         __builtin_amdgcn_global_load_lds((const unsigned*)((const char*)(gbase) + (voff)[_i]), (PG8_LAS unsigned*)(lds + (bufoff) + ldsw + _i * 8192), 16, 0, A_AUX); } while (0)
; #define PG8_LDA(dst, b, h) do { _Pragma("unroll") for (int m = 0; m < 4; ++m) _Pragma("unroll") for (int k = 0; k < 2; ++k) dst[m][k] = *(const PG8_LAS bf16x8*)(lds + PG8_SA(b, h) + aoff + m * 2048 + k * 1024); } while (0)
; #define PG8_LDB(dst, b, h) do { _Pragma("unroll") for (int n = 0; n < 2; ++n) _Pragma("unroll") for (int k = 0; k < 2; ++k) dst[n][k] = *(const PG8_LAS bf16x8*)(lds + PG8_SB(b, h) + boff + n * 2048 + k * 1024); } while (0)
; #define PG8_MMA(ai, bj, At, Bt) do { __builtin_amdgcn_s_setprio(1); _Pragma("unroll") for (int m = 0; m < 4; ++m) _Pragma("unroll") for (int n = 0; n < 2; ++n) _Pragma("unroll") for (int k = 0; k < 2; ++k) \
;         acc[ai][bj][m][n] = __builtin_amdgcn_mfma_f32_16x16x32_bf16(Bt[n][k], At[m][k], acc[ai][bj][m][n], 0, 0, 0); __builtin_amdgcn_s_setprio(0); } while (0)
; #define PG8_WAIT_V(n) asm volatile("s_waitcnt vmcnt(" #n ")" ::: "memory")
; #define PG8_WAIT_L(n) asm volatile("s_waitcnt lgkmcnt(" #n ")" ::: "memory")
; #define PG8_BAR __builtin_amdgcn_s_barrier()
; #define PG8_SCHED __builtin_amdgcn_sched_barrier(0)
;     ...
;             PG8_LDB(B0, 0, 0); PG8_LDB(B1, 0, 1); PG8_SCHED; PG8_LDA(At, 0, 0); PG8_STAGEA(PG8_SA(1, 1), a1 + hstep, voffA);
;             PG8_WAIT_V(8); PG8_WAIT_L(0); PG8_BAR; PG8_MMA(0, 0, At, B0); PG8_MMA(0, 1, At, B1); PG8_BAR; PG8_SCHED;
;             PG8_LDA(At, 0, 1); PG8_STAGE(PG8_SB(0, 0), b2, voffB); PG8_STAGE(PG8_SB(0, 1), b2 + hstep, voffB); PG8_STAGEA(PG8_SA(0, 0), a2, voffA);
;             PG8_WAIT_V(8); PG8_WAIT_L(0); PG8_BAR; PG8_MMA(1, 0, At, B0); PG8_MMA(1, 1, At, B1); PG8_BAR; PG8_SCHED;
;             PG8_LDB(B0, 1, 0); PG8_LDB(B1, 1, 1); PG8_SCHED; PG8_LDA(At, 1, 0); PG8_STAGEA(PG8_SA(0, 1), a2 + hstep, voffA);
;             PG8_WAIT_V(8); PG8_WAIT_L(0); PG8_BAR; PG8_MMA(0, 0, At, B0); PG8_MMA(0, 1, At, B1); PG8_BAR; PG8_SCHED;
	s_setprio 1
	s_waitcnt lgkmcnt(0)
	v_mfma_f32_16x16x32_bf16 v[126:129], v[146:149], v[200:203], v[126:129]
	v_mfma_f32_16x16x32_bf16 v[122:125], v[154:157], v[200:203], v[122:125]
	v_mfma_f32_16x16x32_bf16 v[114:117], v[146:149], v[212:215], v[114:117]
	v_mfma_f32_16x16x32_bf16 v[106:109], v[154:157], v[212:215], v[106:109]
	v_mfma_f32_16x16x32_bf16 v[98:101], v[146:149], v[220:223], v[98:101]
	v_mfma_f32_16x16x32_bf16 v[90:93], v[154:157], v[220:223], v[90:93]
	v_mfma_f32_16x16x32_bf16 v[82:85], v[146:149], v[228:231], v[82:85]
	v_mfma_f32_16x16x32_bf16 v[74:77], v[154:157], v[228:231], v[74:77]
	v_mfma_f32_16x16x32_bf16 v[126:129], v[150:153], v[208:211], v[126:129]
	v_mfma_f32_16x16x32_bf16 v[122:125], v[158:161], v[208:211], v[122:125]
	v_mfma_f32_16x16x32_bf16 v[114:117], v[150:153], v[216:219], v[114:117]
	v_mfma_f32_16x16x32_bf16 v[106:109], v[158:161], v[216:219], v[106:109]
	v_mfma_f32_16x16x32_bf16 v[98:101], v[150:153], v[224:227], v[98:101]
	v_mfma_f32_16x16x32_bf16 v[90:93], v[158:161], v[224:227], v[90:93]
	v_mfma_f32_16x16x32_bf16 v[82:85], v[150:153], v[232:235], v[82:85]
	v_mfma_f32_16x16x32_bf16 v[74:77], v[158:161], v[232:235], v[74:77]
	s_setprio 0
	s_setprio 1
	v_mfma_f32_16x16x32_bf16 v[118:121], v[174:177], v[200:203], v[118:121]
	v_mfma_f32_16x16x32_bf16 v[110:113], v[182:185], v[200:203], v[110:113]
	v_mfma_f32_16x16x32_bf16 v[102:105], v[174:177], v[212:215], v[102:105]
	v_mfma_f32_16x16x32_bf16 v[94:97], v[182:185], v[212:215], v[94:97]
	v_mfma_f32_16x16x32_bf16 v[86:89], v[174:177], v[220:223], v[86:89]
	v_mfma_f32_16x16x32_bf16 v[78:81], v[182:185], v[220:223], v[78:81]
	v_mfma_f32_16x16x32_bf16 v[70:73], v[174:177], v[228:231], v[70:73]
	v_mfma_f32_16x16x32_bf16 v[66:69], v[182:185], v[228:231], v[66:69]
	v_mfma_f32_16x16x32_bf16 v[118:121], v[178:181], v[208:211], v[118:121]
	v_mfma_f32_16x16x32_bf16 v[110:113], v[186:189], v[208:211], v[110:113]
	v_mfma_f32_16x16x32_bf16 v[102:105], v[178:181], v[216:219], v[102:105]
	v_mfma_f32_16x16x32_bf16 v[94:97], v[186:189], v[216:219], v[94:97]
	v_mfma_f32_16x16x32_bf16 v[86:89], v[178:181], v[224:227], v[86:89]
	v_mfma_f32_16x16x32_bf16 v[78:81], v[186:189], v[224:227], v[78:81]
	v_mfma_f32_16x16x32_bf16 v[70:73], v[178:181], v[232:235], v[70:73]
	v_mfma_f32_16x16x32_bf16 v[66:69], v[186:189], v[232:235], v[66:69]
	s_setprio 0
	s_barrier
	s_add_i32 s70, s70, s55
	v_lshl_add_u64 v[140:141], s[50:51], 0, v[0:1]
	s_mov_b32 m0, s70
	ds_read_b128 v[200:203], v145 offset:16384
	ds_read_b128 v[208:211], v145 offset:17408
	ds_read_b128 v[212:215], v145 offset:18432
	ds_read_b128 v[216:219], v145 offset:19456
	ds_read_b128 v[220:223], v145 offset:20480
	ds_read_b128 v[224:227], v145 offset:21504
	ds_read_b128 v[228:231], v145 offset:22528
	ds_read_b128 v[232:235], v145 offset:23552
	global_load_lds_dwordx4 v[140:141], off
	s_add_i32 m0, s70, 0x2000
	s_add_u32 s70, s50, 0x40000
	v_lshl_add_u64 v[190:191], s[50:51], 0, v[130:131]
	s_addc_u32 s71, s51, 0
	s_add_i32 s76, s76, s55
	global_load_lds_dwordx4 v[190:191], off
	v_lshl_add_u64 v[236:237], s[70:71], 0, v[0:1]
	s_mov_b32 m0, s76
	v_lshl_add_u64 v[238:239], s[52:53], 0, v[132:133]
	global_load_lds_dwordx4 v[236:237], off
	v_lshl_add_u64 v[236:237], s[70:71], 0, v[130:131]
	s_add_i32 m0, s76, 0x2000
	s_nop 0
	global_load_lds_dwordx4 v[236:237], off
	v_lshl_add_u64 v[236:237], s[52:53], 0, v[134:135]
	s_mov_b32 m0, s56
	s_nop 0
	global_load_lds_dwordx4 v[236:237], off
	s_mov_b32 m0, s57
	s_nop 0
	global_load_lds_dwordx4 v[238:239], off
	s_waitcnt vmcnt(8)
	s_waitcnt lgkmcnt(0)
	s_barrier
	s_setprio 1
	s_waitcnt lgkmcnt(0)
	v_mfma_f32_16x16x32_bf16 v[62:65], v[146:149], v[200:203], v[62:65]
	v_mfma_f32_16x16x32_bf16 v[58:61], v[154:157], v[200:203], v[58:61]
	v_mfma_f32_16x16x32_bf16 v[50:53], v[146:149], v[212:215], v[50:53]
	v_mfma_f32_16x16x32_bf16 v[42:45], v[154:157], v[212:215], v[42:45]
	v_mfma_f32_16x16x32_bf16 v[34:37], v[146:149], v[220:223], v[34:37]
	v_mfma_f32_16x16x32_bf16 v[26:29], v[154:157], v[220:223], v[26:29]
	v_mfma_f32_16x16x32_bf16 v[18:21], v[146:149], v[228:231], v[18:21]
	v_mfma_f32_16x16x32_bf16 v[10:13], v[154:157], v[228:231], v[10:13]
	v_mfma_f32_16x16x32_bf16 v[62:65], v[150:153], v[208:211], v[62:65]
	v_mfma_f32_16x16x32_bf16 v[58:61], v[158:161], v[208:211], v[58:61]
	v_mfma_f32_16x16x32_bf16 v[50:53], v[150:153], v[216:219], v[50:53]
	v_mfma_f32_16x16x32_bf16 v[42:45], v[158:161], v[216:219], v[42:45]
	v_mfma_f32_16x16x32_bf16 v[34:37], v[150:153], v[224:227], v[34:37]
	v_mfma_f32_16x16x32_bf16 v[26:29], v[158:161], v[224:227], v[26:29]
	v_mfma_f32_16x16x32_bf16 v[18:21], v[150:153], v[232:235], v[18:21]
	v_mfma_f32_16x16x32_bf16 v[10:13], v[158:161], v[232:235], v[10:13]
	s_setprio 0
	s_setprio 1
	v_mfma_f32_16x16x32_bf16 v[54:57], v[174:177], v[200:203], v[54:57]
	v_mfma_f32_16x16x32_bf16 v[46:49], v[182:185], v[200:203], v[46:49]
	v_mfma_f32_16x16x32_bf16 v[38:41], v[174:177], v[212:215], v[38:41]
	v_mfma_f32_16x16x32_bf16 v[30:33], v[182:185], v[212:215], v[30:33]
	v_mfma_f32_16x16x32_bf16 v[22:25], v[174:177], v[220:223], v[22:25]
	v_mfma_f32_16x16x32_bf16 v[14:17], v[182:185], v[220:223], v[14:17]
	v_mfma_f32_16x16x32_bf16 v[6:9], v[174:177], v[228:231], v[6:9]
	v_mfma_f32_16x16x32_bf16 v[2:5], v[182:185], v[228:231], v[2:5]
	v_mfma_f32_16x16x32_bf16 v[54:57], v[178:181], v[208:211], v[54:57]
	v_mfma_f32_16x16x32_bf16 v[46:49], v[186:189], v[208:211], v[46:49]
	v_mfma_f32_16x16x32_bf16 v[38:41], v[178:181], v[216:219], v[38:41]
	v_mfma_f32_16x16x32_bf16 v[30:33], v[186:189], v[216:219], v[30:33]
	v_mfma_f32_16x16x32_bf16 v[22:25], v[178:181], v[224:227], v[22:25]
	v_mfma_f32_16x16x32_bf16 v[14:17], v[186:189], v[224:227], v[14:17]
	v_mfma_f32_16x16x32_bf16 v[6:9], v[178:181], v[232:235], v[6:9]
	v_mfma_f32_16x16x32_bf16 v[2:5], v[186:189], v[232:235], v[2:5]
	s_setprio 0
	s_barrier
; #define PG8_STAGEA(bufoff, gbase, voff) do { _Pragma("unroll") for (int _i = 0; _i < 2; ++_i) \
;         __builtin_amdgcn_global_load_lds((const unsigned*)((const char*)(gbase) + (voff)[_i]), (PG8_LAS unsigned*)(lds + (bufoff) + ldsw + _i * 8192), 16, 0, A_AUX); } while (0)
; #define PG8_LDA(dst, b, h) do { _Pragma("unroll") for (int m = 0; m < 4; ++m) _Pragma("unroll") for (int k = 0; k < 2; ++k) dst[m][k] = *(const PG8_LAS bf16x8*)(lds + PG8_SA(b, h) + aoff + m * 2048 + k * 1024); } while (0)
; #define PG8_LDB(dst, b, h) do { _Pragma("unroll") for (int n = 0; n < 2; ++n) _Pragma("unroll") for (int k = 0; k < 2; ++k) dst[n][k] = *(const PG8_LAS bf16x8*)(lds + PG8_SB(b, h) + boff + n * 2048 + k * 1024); } while (0)
; #define PG8_MMA(ai, bj, At, Bt) do { __builtin_amdgcn_s_setprio(1); _Pragma("unroll") for (int m = 0; m < 4; ++m) _Pragma("unroll") for (int n = 0; n < 2; ++n) _Pragma("unroll") for (int k = 0; k < 2; ++k) \
;         acc[ai][bj][m][n] = __builtin_amdgcn_mfma_f32_16x16x32_bf16(Bt[n][k], At[m][k], acc[ai][bj][m][n], 0, 0, 0); __builtin_amdgcn_s_setprio(0); } while (0)
; #define PG8_WAIT_V(n) asm volatile("s_waitcnt vmcnt(" #n ")" ::: "memory")
; #define PG8_WAIT_L(n) asm volatile("s_waitcnt lgkmcnt(" #n ")" ::: "memory")
; #define PG8_BAR __builtin_amdgcn_s_barrier()
; #define PG8_SCHED __builtin_amdgcn_sched_barrier(0)
;     ...
;             PG8_LDB(B0, 1, 0); PG8_LDB(B1, 1, 1); PG8_SCHED; PG8_LDA(At, 1, 0); PG8_STAGEA(PG8_SA(0, 1), a2 + hstep, voffA);
;             PG8_WAIT_V(8); PG8_WAIT_L(0); PG8_BAR; PG8_MMA(0, 0, At, B0); PG8_MMA(0, 1, At, B1); PG8_BAR; PG8_SCHED;
	s_add_i32 s70, 0, 0x18000
	s_add_i32 s71, 0, 0x1c000
	v_add_u32_e32 v158, s70, v143
	v_add_u32_e32 v186, s71, v143
	ds_read_b128 v[146:149], v158
	ds_read_b128 v[150:153], v158 offset:1024
	ds_read_b128 v[154:157], v158 offset:2048
	ds_read_b128 v[158:161], v158 offset:3072
	ds_read_b128 v[174:177], v186
	ds_read_b128 v[178:181], v186 offset:1024
	ds_read_b128 v[182:185], v186 offset:2048
	ds_read_b128 v[186:189], v186 offset:3072
	s_add_u32 s52, s52, 0x40000
	s_addc_u32 s53, s53, 0
	s_mov_b32 m0, s58
	v_lshl_add_u64 v[240:241], s[52:53], 0, v[134:135]
	ds_read_b128 v[200:203], v145 offset:32768
	ds_read_b128 v[208:211], v145 offset:33792
	ds_read_b128 v[212:215], v145 offset:34816
	ds_read_b128 v[216:219], v145 offset:35840
	ds_read_b128 v[220:223], v145 offset:36864
	ds_read_b128 v[224:227], v145 offset:37888
	ds_read_b128 v[228:231], v145 offset:38912
	ds_read_b128 v[232:235], v145 offset:39936
	global_load_lds_dwordx4 v[240:241], off
	v_lshl_add_u64 v[240:241], s[52:53], 0, v[132:133]
	s_mov_b32 m0, s59
	s_nop 0
	global_load_lds_dwordx4 v[240:241], off
	s_waitcnt vmcnt(8)
	s_waitcnt lgkmcnt(0)
	s_barrier
	s_setprio 1
	s_waitcnt lgkmcnt(0)
	v_mfma_f32_16x16x32_bf16 v[126:129], v[146:149], v[200:203], v[126:129]
	v_mfma_f32_16x16x32_bf16 v[122:125], v[154:157], v[200:203], v[122:125]
	v_mfma_f32_16x16x32_bf16 v[114:117], v[146:149], v[212:215], v[114:117]
	v_mfma_f32_16x16x32_bf16 v[106:109], v[154:157], v[212:215], v[106:109]
	v_mfma_f32_16x16x32_bf16 v[98:101], v[146:149], v[220:223], v[98:101]
	v_mfma_f32_16x16x32_bf16 v[90:93], v[154:157], v[220:223], v[90:93]
	v_mfma_f32_16x16x32_bf16 v[82:85], v[146:149], v[228:231], v[82:85]
	v_mfma_f32_16x16x32_bf16 v[74:77], v[154:157], v[228:231], v[74:77]
	v_mfma_f32_16x16x32_bf16 v[126:129], v[150:153], v[208:211], v[126:129]
	v_mfma_f32_16x16x32_bf16 v[122:125], v[158:161], v[208:211], v[122:125]
	v_mfma_f32_16x16x32_bf16 v[114:117], v[150:153], v[216:219], v[114:117]
	v_mfma_f32_16x16x32_bf16 v[106:109], v[158:161], v[216:219], v[106:109]
	v_mfma_f32_16x16x32_bf16 v[98:101], v[150:153], v[224:227], v[98:101]
	v_mfma_f32_16x16x32_bf16 v[90:93], v[158:161], v[224:227], v[90:93]
	v_mfma_f32_16x16x32_bf16 v[82:85], v[150:153], v[232:235], v[82:85]
	v_mfma_f32_16x16x32_bf16 v[74:77], v[158:161], v[232:235], v[74:77]
	s_setprio 0
	s_setprio 1
	v_mfma_f32_16x16x32_bf16 v[118:121], v[174:177], v[200:203], v[118:121]
	v_mfma_f32_16x16x32_bf16 v[110:113], v[182:185], v[200:203], v[110:113]
	v_mfma_f32_16x16x32_bf16 v[102:105], v[174:177], v[212:215], v[102:105]
	v_mfma_f32_16x16x32_bf16 v[94:97], v[182:185], v[212:215], v[94:97]
	v_mfma_f32_16x16x32_bf16 v[86:89], v[174:177], v[220:223], v[86:89]
	v_mfma_f32_16x16x32_bf16 v[78:81], v[182:185], v[220:223], v[78:81]
	v_mfma_f32_16x16x32_bf16 v[70:73], v[174:177], v[228:231], v[70:73]
	v_mfma_f32_16x16x32_bf16 v[66:69], v[182:185], v[228:231], v[66:69]
	v_mfma_f32_16x16x32_bf16 v[118:121], v[178:181], v[208:211], v[118:121]
	v_mfma_f32_16x16x32_bf16 v[110:113], v[186:189], v[208:211], v[110:113]
	v_mfma_f32_16x16x32_bf16 v[102:105], v[178:181], v[216:219], v[102:105]
	v_mfma_f32_16x16x32_bf16 v[94:97], v[186:189], v[216:219], v[94:97]
	v_mfma_f32_16x16x32_bf16 v[86:89], v[178:181], v[224:227], v[86:89]
	v_mfma_f32_16x16x32_bf16 v[78:81], v[186:189], v[224:227], v[78:81]
	v_mfma_f32_16x16x32_bf16 v[70:73], v[178:181], v[232:235], v[70:73]
	v_mfma_f32_16x16x32_bf16 v[66:69], v[186:189], v[232:235], v[66:69]
	s_setprio 0
	s_barrier
; #define PG8_STAGE(bufoff, gbase, voff) do { _Pragma("unroll") for (int _i = 0; _i < 2; ++_i) \
;         __builtin_amdgcn_global_load_lds((const unsigned*)((const char*)(gbase) + (voff)[_i]), (PG8_LAS unsigned*)(lds + (bufoff) + ldsw + _i * 8192), 16, 0, 0); } while (0)
; #define PG8_STAGEA(bufoff, gbase, voff) do { _Pragma("unroll") for (int _i = 0; _i < 2; ++_i) \
;         __builtin_amdgcn_global_load_lds((const unsigned*)((const char*)(gbase) + (voff)[_i]), (PG8_LAS unsigned*)(lds + (bufoff) + ldsw + _i * 8192), 16, 0, A_AUX); } while (0)
; #define PG8_LDA(dst, b, h) do { _Pragma("unroll") for (int m = 0; m < 4; ++m) _Pragma("unroll") for (int k = 0; k < 2; ++k) dst[m][k] = *(const PG8_LAS bf16x8*)(lds + PG8_SA(b, h) + aoff + m * 2048 + k * 1024); } while (0)
; #define PG8_WAIT_V(n) asm volatile("s_waitcnt vmcnt(" #n ")" ::: "memory")
; #define PG8_BAR __builtin_amdgcn_s_barrier()
;     ...
;         for (int t = 0; t < nt; t += 2) {
;             const bool last = (t == nt - 2);
;             const char* a1 = cA + (size_t)(t + 1) * kstep;
;             const char* a2 = last ? nA : cA + (size_t)(t + 2) * kstep; const char* b2 = last ? nB : cB + (size_t)(t + 2) * kstep;
;             const char* a3 = a2 + kstep; const char* b3 = b2 + kstep;
;             if (last && has_next) S.a_ready(nxt);
;             if constexpr (SP2) {
;             PG8_LDB(B0, 0, 0); PG8_LDB(B1, 0, 1); PG8_SCHED; PG8_LDA(At, 0, 0); PG8_STAGEA(PG8_SA(1, 1), a1 + hstep, voffA);
;             PG8_WAIT_V(8); PG8_WAIT_L(0); PG8_BAR; PG8_MMA(0, 0, At, B0); PG8_MMA(0, 1, At, B1); PG8_BAR; PG8_SCHED;
;             PG8_LDA(At, 0, 1); PG8_STAGE(PG8_SB(0, 0), b2, voffB); PG8_STAGE(PG8_SB(0, 1), b2 + hstep, voffB); PG8_STAGEA(PG8_SA(0, 0), a2, voffA);
;             PG8_WAIT_V(8); PG8_WAIT_L(0); PG8_BAR; PG8_MMA(1, 0, At, B0); PG8_MMA(1, 1, At, B1); PG8_BAR; PG8_SCHED;
;             PG8_LDB(B0, 1, 0); PG8_LDB(B1, 1, 1); PG8_SCHED; PG8_LDA(At, 1, 0); PG8_STAGEA(PG8_SA(0, 1), a2 + hstep, voffA);
;             PG8_WAIT_V(8); PG8_WAIT_L(0); PG8_BAR; PG8_MMA(0, 0, At, B0); PG8_MMA(0, 1, At, B1); PG8_BAR; PG8_SCHED;
;             PG8_LDA(At, 1, 1); PG8_STAGE(PG8_SB(1, 0), b3, voffB); PG8_STAGE(PG8_SB(1, 1), b3 + hstep, voffB); PG8_STAGEA(PG8_SA(1, 0), a3, voffA);
;             PG8_WAIT_V(8); PG8_WAIT_L(0); PG8_BAR; PG8_MMA(1, 0, At, B0); PG8_MMA(1, 1, At, B1); PG8_BAR; PG8_SCHED;
	s_add_i32 s52, s70, s55
	v_lshl_add_u64 v[140:141], v[140:141], 0, s[8:9]
	s_mov_b32 m0, s52
	ds_read_b128 v[200:203], v145 offset:49152
	ds_read_b128 v[208:211], v145 offset:50176
	ds_read_b128 v[212:215], v145 offset:51200
	ds_read_b128 v[216:219], v145 offset:52224
	ds_read_b128 v[220:223], v145 offset:53248
	ds_read_b128 v[224:227], v145 offset:54272
	ds_read_b128 v[228:231], v145 offset:55296
	ds_read_b128 v[232:235], v145 offset:56320
	global_load_lds_dwordx4 v[140:141], off
	s_add_i32 m0, s52, 0x2000
	s_add_u32 s50, s50, 0x40080
	v_lshl_add_u64 v[140:141], v[190:191], 0, s[8:9]
	s_addc_u32 s51, s51, 0
	s_add_i32 s52, s71, s55
	global_load_lds_dwordx4 v[140:141], off
	v_lshl_add_u64 v[140:141], s[50:51], 0, v[0:1]
	s_mov_b32 m0, s52
	s_nop 0
	global_load_lds_dwordx4 v[140:141], off
	v_lshl_add_u64 v[140:141], s[50:51], 0, v[130:131]
	s_add_i32 m0, s52, 0x2000
	s_nop 0
	global_load_lds_dwordx4 v[140:141], off
	v_lshl_add_u64 v[140:141], v[236:237], 0, s[8:9]
	s_mov_b32 m0, s60
	s_nop 0
	global_load_lds_dwordx4 v[140:141], off
	v_lshl_add_u64 v[140:141], v[238:239], 0, s[8:9]
	s_mov_b32 m0, s61
	s_nop 0
	global_load_lds_dwordx4 v[140:141], off
	s_waitcnt vmcnt(8)
	s_waitcnt lgkmcnt(0)
	s_barrier
	s_setprio 1
	s_waitcnt lgkmcnt(0)
	v_mfma_f32_16x16x32_bf16 v[62:65], v[146:149], v[200:203], v[62:65]
	v_mfma_f32_16x16x32_bf16 v[58:61], v[154:157], v[200:203], v[58:61]
	v_mfma_f32_16x16x32_bf16 v[50:53], v[146:149], v[212:215], v[50:53]
	v_mfma_f32_16x16x32_bf16 v[42:45], v[154:157], v[212:215], v[42:45]
	v_mfma_f32_16x16x32_bf16 v[34:37], v[146:149], v[220:223], v[34:37]
	v_mfma_f32_16x16x32_bf16 v[26:29], v[154:157], v[220:223], v[26:29]
	v_mfma_f32_16x16x32_bf16 v[18:21], v[146:149], v[228:231], v[18:21]
	v_mfma_f32_16x16x32_bf16 v[10:13], v[154:157], v[228:231], v[10:13]
	v_mfma_f32_16x16x32_bf16 v[62:65], v[150:153], v[208:211], v[62:65]
	v_mfma_f32_16x16x32_bf16 v[58:61], v[158:161], v[208:211], v[58:61]
	v_mfma_f32_16x16x32_bf16 v[50:53], v[150:153], v[216:219], v[50:53]
	v_mfma_f32_16x16x32_bf16 v[42:45], v[158:161], v[216:219], v[42:45]
	v_mfma_f32_16x16x32_bf16 v[34:37], v[150:153], v[224:227], v[34:37]
	v_mfma_f32_16x16x32_bf16 v[26:29], v[158:161], v[224:227], v[26:29]
	v_mfma_f32_16x16x32_bf16 v[18:21], v[150:153], v[232:235], v[18:21]
	v_mfma_f32_16x16x32_bf16 v[10:13], v[158:161], v[232:235], v[10:13]
	s_setprio 0
	s_setprio 1
	v_mfma_f32_16x16x32_bf16 v[54:57], v[174:177], v[200:203], v[54:57]
	v_mfma_f32_16x16x32_bf16 v[46:49], v[182:185], v[200:203], v[46:49]
	v_mfma_f32_16x16x32_bf16 v[38:41], v[174:177], v[212:215], v[38:41]
	v_mfma_f32_16x16x32_bf16 v[30:33], v[182:185], v[212:215], v[30:33]
	s_add_i32 s73, s73, 2
	s_add_u32 s48, s48, 0x100
	s_addc_u32 s49, s49, 0
	s_add_u32 s65, s65, 0x100
	s_addc_u32 s72, s72, 0
	s_add_u32 s50, s48, 0xfffc0080
	s_addc_u32 s51, s49, -1
	s_add_i32 s70, 0, 0x10000
	s_cmp_eq_u32 s73, 12
	s_cselect_b32 s53, s16, s51
	s_cselect_b32 s52, s17, s50
	s_cselect_b32 s51, s41, s72
	s_cselect_b32 s50, s43, s65
	s_add_i32 s76, 0, 0x14000
	v_mfma_f32_16x16x32_bf16 v[22:25], v[174:177], v[220:223], v[22:25]
	v_mfma_f32_16x16x32_bf16 v[14:17], v[182:185], v[220:223], v[14:17]
	v_mfma_f32_16x16x32_bf16 v[6:9], v[174:177], v[228:231], v[6:9]
	v_mfma_f32_16x16x32_bf16 v[2:5], v[182:185], v[228:231], v[2:5]
	v_mfma_f32_16x16x32_bf16 v[54:57], v[178:181], v[208:211], v[54:57]
	v_mfma_f32_16x16x32_bf16 v[46:49], v[186:189], v[208:211], v[46:49]
	v_mfma_f32_16x16x32_bf16 v[38:41], v[178:181], v[216:219], v[38:41]
	v_mfma_f32_16x16x32_bf16 v[30:33], v[186:189], v[216:219], v[30:33]
	v_mfma_f32_16x16x32_bf16 v[22:25], v[178:181], v[224:227], v[22:25]
	v_mfma_f32_16x16x32_bf16 v[14:17], v[186:189], v[224:227], v[14:17]
	v_mfma_f32_16x16x32_bf16 v[6:9], v[178:181], v[232:235], v[6:9]
	v_mfma_f32_16x16x32_bf16 v[2:5], v[186:189], v[232:235], v[2:5]
	s_setprio 0
	s_barrier
	s_cmp_gt_u32 s73, 13
	s_cbranch_scc0 .LBB0_443
	s_and_b64 vcc, exec, s[36:37]
	s_cbranch_vccz .LBB0_446
	s_barrier

; #define PG8_STAGE(bufoff, gbase, voff) do { _Pragma("unroll") for (int _i = 0; _i < 2; ++_i) \
;         __builtin_amdgcn_global_load_lds((const unsigned*)((const char*)(gbase) + (voff)[_i]), (PG8_LAS unsigned*)(lds + (bufoff) + ldsw + _i * 8192), 16, 0, 0); } while (0)
; #define PG8_STAGEA(bufoff, gbase, voff) do { _Pragma("unroll") for (int _i = 0; _i < 2; ++_i) \
;         __builtin_amdgcn_global_load_lds((const unsigned*)((const char*)(gbase) + (voff)[_i]), (PG8_LAS unsigned*)(lds + (bufoff) + ldsw + _i * 8192), 16, 0, A_AUX); } while (0)
; #define PG8_LDA(dst, b, h) do { _Pragma("unroll") for (int m = 0; m < 4; ++m) _Pragma("unroll") for (int k = 0; k < 2; ++k) dst[m][k] = *(const PG8_LAS bf16x8*)(lds + PG8_SA(b, h) + aoff + m * 2048 + k * 1024); } while (0)
; #define PG8_LDB(dst, b, h) do { _Pragma("unroll") for (int n = 0; n < 2; ++n) _Pragma("unroll") for (int k = 0; k < 2; ++k) dst[n][k] = *(const PG8_LAS bf16x8*)(lds + PG8_SB(b, h) + boff + n * 2048 + k * 1024); } while (0)
; #define PG8_WAIT_V(n) asm volatile("s_waitcnt vmcnt(" #n ")" ::: "memory")
; #define PG8_WAIT_L(n) asm volatile("s_waitcnt lgkmcnt(" #n ")" ::: "memory")
; #define PG8_BAR __builtin_amdgcn_s_barrier()
;     ...
;         const bool has_next = S.next(ui + 1, nxt);
;         const char* nA = has_next ? (const char*)g.A + (size_t)nxt.pm * tstep : cA; const char* nB = has_next ? (const char*)g.Bt + (size_t)nxt.pn * tstep : cB;
;         for (int t = 0; t < nt; t += 2) {
;             const bool last = (t == nt - 2);
;             const char* a1 = cA + (size_t)(t + 1) * kstep;
;             const char* a2 = last ? nA : cA + (size_t)(t + 2) * kstep; const char* b2 = last ? nB : cB + (size_t)(t + 2) * kstep;
;             const char* a3 = a2 + kstep; const char* b3 = b2 + kstep;
;             if (last && has_next) S.a_ready(nxt);
;             if constexpr (SP2) {
;             PG8_LDB(B0, 0, 0); PG8_LDB(B1, 0, 1); PG8_SCHED; PG8_LDA(At, 0, 0); PG8_STAGEA(PG8_SA(1, 1), a1 + hstep, voffA);
;             PG8_WAIT_V(8); PG8_WAIT_L(0); PG8_BAR; PG8_MMA(0, 0, At, B0); PG8_MMA(0, 1, At, B1); PG8_BAR; PG8_SCHED;
;             PG8_LDA(At, 0, 1); PG8_STAGE(PG8_SB(0, 0), b2, voffB); PG8_STAGE(PG8_SB(0, 1), b2 + hstep, voffB); PG8_STAGEA(PG8_SA(0, 0), a2, voffA);
;             PG8_WAIT_V(8); PG8_WAIT_L(0); PG8_BAR; PG8_MMA(1, 0, At, B0); PG8_MMA(1, 1, At, B1); PG8_BAR; PG8_SCHED;
.LBB0_655:
	s_add_u32 s16, s48, 0x100
	s_addc_u32 s17, s49, 0
	s_mov_b32 s73, -2
	s_add_u32 s48, s46, 0x100
	s_addc_u32 s49, s47, 0
	s_add_i32 s70, 0, 0x10000
	s_cmp_eq_u32 s73, 40
	s_cselect_b32 s53, s1, s49
	s_cselect_b32 s52, s0, s48
	s_cselect_b32 s51, s45, s17
	s_cselect_b32 s50, s44, s16
	s_add_i32 s71, 0, 0x14000
	v_add_u32_e32 v140, s70, v143
	ds_read_b128 v[146:149], v140
	ds_read_b128 v[150:153], v140 offset:1024
	ds_read_b128 v[154:157], v140 offset:2048
	ds_read_b128 v[158:161], v140 offset:3072
	v_add_u32_e32 v140, s71, v143
	ds_read_b128 v[174:177], v140
	ds_read_b128 v[178:181], v140 offset:1024
	ds_read_b128 v[182:185], v140 offset:2048
	ds_read_b128 v[186:189], v140 offset:3072
	v_lshl_add_u64 v[140:141], s[46:47], 0, v[136:137]
	s_add_i32 m0, s56, 0xc000
	ds_read_b128 v[200:203], v145
	ds_read_b128 v[208:211], v145 offset:1024
	ds_read_b128 v[212:215], v145 offset:2048
	ds_read_b128 v[216:219], v145 offset:3072
	ds_read_b128 v[220:223], v145 offset:4096
	ds_read_b128 v[224:227], v145 offset:5120
	ds_read_b128 v[228:231], v145 offset:6144
	ds_read_b128 v[232:235], v145 offset:7168
	global_load_lds_dwordx4 v[140:141], off
	v_lshl_add_u64 v[140:141], s[46:47], 0, v[138:139]
	s_add_i32 m0, s56, 0xe000
	s_nop 0
	global_load_lds_dwordx4 v[140:141], off
	s_waitcnt vmcnt(8)
	s_waitcnt lgkmcnt(0)
	s_barrier
	s_setprio 1
	s_waitcnt lgkmcnt(0)
	v_mfma_f32_16x16x32_bf16 v[126:129], v[146:149], v[200:203], 0
	v_mfma_f32_16x16x32_bf16 v[122:125], v[154:157], v[200:203], 0
	v_mfma_f32_16x16x32_bf16 v[114:117], v[146:149], v[212:215], 0
	v_mfma_f32_16x16x32_bf16 v[106:109], v[154:157], v[212:215], 0
	v_mfma_f32_16x16x32_bf16 v[98:101], v[146:149], v[220:223], 0
	v_mfma_f32_16x16x32_bf16 v[90:93], v[154:157], v[220:223], 0
	v_mfma_f32_16x16x32_bf16 v[82:85], v[146:149], v[228:231], 0
	v_mfma_f32_16x16x32_bf16 v[74:77], v[154:157], v[228:231], 0
	v_mfma_f32_16x16x32_bf16 v[126:129], v[150:153], v[208:211], v[126:129]
	v_mfma_f32_16x16x32_bf16 v[122:125], v[158:161], v[208:211], v[122:125]
	v_mfma_f32_16x16x32_bf16 v[114:117], v[150:153], v[216:219], v[114:117]
	v_mfma_f32_16x16x32_bf16 v[106:109], v[158:161], v[216:219], v[106:109]
	v_mfma_f32_16x16x32_bf16 v[98:101], v[150:153], v[224:227], v[98:101]
	v_mfma_f32_16x16x32_bf16 v[90:93], v[158:161], v[224:227], v[90:93]
	v_mfma_f32_16x16x32_bf16 v[82:85], v[150:153], v[232:235], v[82:85]
	v_mfma_f32_16x16x32_bf16 v[74:77], v[158:161], v[232:235], v[74:77]
	s_setprio 0
	s_setprio 1
	v_mfma_f32_16x16x32_bf16 v[118:121], v[174:177], v[200:203], 0
	v_mfma_f32_16x16x32_bf16 v[110:113], v[182:185], v[200:203], 0
	v_mfma_f32_16x16x32_bf16 v[102:105], v[174:177], v[212:215], 0
	v_mfma_f32_16x16x32_bf16 v[94:97], v[182:185], v[212:215], 0
	v_mfma_f32_16x16x32_bf16 v[86:89], v[174:177], v[220:223], 0
	v_mfma_f32_16x16x32_bf16 v[78:81], v[182:185], v[220:223], 0
	v_mfma_f32_16x16x32_bf16 v[70:73], v[174:177], v[228:231], 0
	v_mfma_f32_16x16x32_bf16 v[66:69], v[182:185], v[228:231], 0
	v_mfma_f32_16x16x32_bf16 v[118:121], v[178:181], v[208:211], v[118:121]
	v_mfma_f32_16x16x32_bf16 v[110:113], v[186:189], v[208:211], v[110:113]
	v_mfma_f32_16x16x32_bf16 v[102:105], v[178:181], v[216:219], v[102:105]
	v_mfma_f32_16x16x32_bf16 v[94:97], v[186:189], v[216:219], v[94:97]
	v_mfma_f32_16x16x32_bf16 v[86:89], v[178:181], v[224:227], v[86:89]
	v_mfma_f32_16x16x32_bf16 v[78:81], v[186:189], v[224:227], v[78:81]
	v_mfma_f32_16x16x32_bf16 v[70:73], v[178:181], v[232:235], v[70:73]
	v_mfma_f32_16x16x32_bf16 v[66:69], v[186:189], v[232:235], v[66:69]
	s_setprio 0
	s_barrier
	s_add_i32 s46, s70, s55
	v_lshl_add_u64 v[140:141], s[50:51], 0, v[0:1]
	s_mov_b32 m0, s46
	ds_read_b128 v[200:203], v145 offset:16384
	ds_read_b128 v[208:211], v145 offset:17408
	ds_read_b128 v[212:215], v145 offset:18432
	ds_read_b128 v[216:219], v145 offset:19456
	ds_read_b128 v[220:223], v145 offset:20480
	ds_read_b128 v[224:227], v145 offset:21504
	ds_read_b128 v[228:231], v145 offset:22528
	ds_read_b128 v[232:235], v145 offset:23552
	global_load_lds_dwordx4 v[140:141], off
	s_add_i32 m0, s46, 0x2000
	s_add_u32 s46, s50, 0xb0000
	v_lshl_add_u64 v[190:191], s[50:51], 0, v[130:131]
	s_addc_u32 s47, s51, 0
	s_add_i32 s70, s71, s55
	global_load_lds_dwordx4 v[190:191], off
	v_lshl_add_u64 v[236:237], s[46:47], 0, v[0:1]
	s_mov_b32 m0, s70
	v_lshl_add_u64 v[238:239], s[52:53], 0, v[132:133]
	global_load_lds_dwordx4 v[236:237], off
	v_lshl_add_u64 v[236:237], s[46:47], 0, v[130:131]
	s_add_i32 m0, s70, 0x2000
	s_nop 0
	global_load_lds_dwordx4 v[236:237], off
	v_lshl_add_u64 v[236:237], s[52:53], 0, v[134:135]
	s_mov_b32 m0, s56
	s_nop 0
	global_load_lds_dwordx4 v[236:237], off
	s_mov_b32 m0, s57
	s_nop 0
	global_load_lds_dwordx4 v[238:239], off
	s_waitcnt vmcnt(8)
	s_waitcnt lgkmcnt(0)
	s_barrier
; #define PG8_STAGEA(bufoff, gbase, voff) do { _Pragma("unroll") for (int _i = 0; _i < 2; ++_i) \
;         __builtin_amdgcn_global_load_lds((const unsigned*)((const char*)(gbase) + (voff)[_i]), (PG8_LAS unsigned*)(lds + (bufoff) + ldsw + _i * 8192), 16, 0, A_AUX); } while (0)
; #define PG8_LDA(dst, b, h) do { _Pragma("unroll") for (int m = 0; m < 4; ++m) _Pragma("unroll") for (int k = 0; k < 2; ++k) dst[m][k] = *(const PG8_LAS bf16x8*)(lds + PG8_SA(b, h) + aoff + m * 2048 + k * 1024); } while (0)
; #define PG8_LDB(dst, b, h) do { _Pragma("unroll") for (int n = 0; n < 2; ++n) _Pragma("unroll") for (int k = 0; k < 2; ++k) dst[n][k] = *(const PG8_LAS bf16x8*)(lds + PG8_SB(b, h) + boff + n * 2048 + k * 1024); } while (0)
; #define PG8_MMA(ai, bj, At, Bt) do { __builtin_amdgcn_s_setprio(1); _Pragma("unroll") for (int m = 0; m < 4; ++m) _Pragma("unroll") for (int n = 0; n < 2; ++n) _Pragma("unroll") for (int k = 0; k < 2; ++k) \
;         acc[ai][bj][m][n] = __builtin_amdgcn_mfma_f32_16x16x32_bf16(Bt[n][k], At[m][k], acc[ai][bj][m][n], 0, 0, 0); __builtin_amdgcn_s_setprio(0); } while (0)
; #define PG8_WAIT_V(n) asm volatile("s_waitcnt vmcnt(" #n ")" ::: "memory")
; #define PG8_WAIT_L(n) asm volatile("s_waitcnt lgkmcnt(" #n ")" ::: "memory")
; #define PG8_BAR __builtin_amdgcn_s_barrier()
; #define PG8_SCHED __builtin_amdgcn_sched_barrier(0)
;     ...
;             PG8_WAIT_V(8); PG8_WAIT_L(0); PG8_BAR; PG8_MMA(1, 0, At, B0); PG8_MMA(1, 1, At, B1); PG8_BAR; PG8_SCHED;
;             PG8_LDB(B0, 1, 0); PG8_LDB(B1, 1, 1); PG8_SCHED; PG8_LDA(At, 1, 0); PG8_STAGEA(PG8_SA(0, 1), a2 + hstep, voffA);
;             PG8_WAIT_V(8); PG8_WAIT_L(0); PG8_BAR; PG8_MMA(0, 0, At, B0); PG8_MMA(0, 1, At, B1); PG8_BAR; PG8_SCHED;
	s_setprio 1
	s_waitcnt lgkmcnt(0)
	v_mfma_f32_16x16x32_bf16 v[62:65], v[146:149], v[200:203], 0
	v_mfma_f32_16x16x32_bf16 v[58:61], v[154:157], v[200:203], 0
	v_mfma_f32_16x16x32_bf16 v[50:53], v[146:149], v[212:215], 0
	v_mfma_f32_16x16x32_bf16 v[42:45], v[154:157], v[212:215], 0
	v_mfma_f32_16x16x32_bf16 v[34:37], v[146:149], v[220:223], 0
	v_mfma_f32_16x16x32_bf16 v[26:29], v[154:157], v[220:223], 0
	v_mfma_f32_16x16x32_bf16 v[18:21], v[146:149], v[228:231], 0
	v_mfma_f32_16x16x32_bf16 v[10:13], v[154:157], v[228:231], 0
	v_mfma_f32_16x16x32_bf16 v[62:65], v[150:153], v[208:211], v[62:65]
	v_mfma_f32_16x16x32_bf16 v[58:61], v[158:161], v[208:211], v[58:61]
	v_mfma_f32_16x16x32_bf16 v[50:53], v[150:153], v[216:219], v[50:53]
	v_mfma_f32_16x16x32_bf16 v[42:45], v[158:161], v[216:219], v[42:45]
	v_mfma_f32_16x16x32_bf16 v[34:37], v[150:153], v[224:227], v[34:37]
	v_mfma_f32_16x16x32_bf16 v[26:29], v[158:161], v[224:227], v[26:29]
	v_mfma_f32_16x16x32_bf16 v[18:21], v[150:153], v[232:235], v[18:21]
	v_mfma_f32_16x16x32_bf16 v[10:13], v[158:161], v[232:235], v[10:13]
	s_setprio 0
	s_setprio 1
	v_mfma_f32_16x16x32_bf16 v[54:57], v[174:177], v[200:203], 0
	v_mfma_f32_16x16x32_bf16 v[46:49], v[182:185], v[200:203], 0
	v_mfma_f32_16x16x32_bf16 v[38:41], v[174:177], v[212:215], 0
	v_mfma_f32_16x16x32_bf16 v[30:33], v[182:185], v[212:215], 0
	v_mfma_f32_16x16x32_bf16 v[22:25], v[174:177], v[220:223], 0
	v_mfma_f32_16x16x32_bf16 v[14:17], v[182:185], v[220:223], 0
	v_mfma_f32_16x16x32_bf16 v[6:9], v[174:177], v[228:231], 0
	v_mfma_f32_16x16x32_bf16 v[2:5], v[182:185], v[228:231], 0
	v_mfma_f32_16x16x32_bf16 v[54:57], v[178:181], v[208:211], v[54:57]
	v_mfma_f32_16x16x32_bf16 v[46:49], v[186:189], v[208:211], v[46:49]
	v_mfma_f32_16x16x32_bf16 v[38:41], v[178:181], v[216:219], v[38:41]
	v_mfma_f32_16x16x32_bf16 v[30:33], v[186:189], v[216:219], v[30:33]
	v_mfma_f32_16x16x32_bf16 v[22:25], v[178:181], v[224:227], v[22:25]
	v_mfma_f32_16x16x32_bf16 v[14:17], v[186:189], v[224:227], v[14:17]
	v_mfma_f32_16x16x32_bf16 v[6:9], v[178:181], v[232:235], v[6:9]
	v_mfma_f32_16x16x32_bf16 v[2:5], v[186:189], v[232:235], v[2:5]
	s_setprio 0
	s_barrier
	s_add_i32 s70, 0, 0x18000
	s_add_i32 s71, 0, 0x1c000
	v_add_u32_e32 v158, s70, v143
	v_add_u32_e32 v186, s71, v143
	ds_read_b128 v[146:149], v158
	ds_read_b128 v[150:153], v158 offset:1024
	ds_read_b128 v[154:157], v158 offset:2048
	ds_read_b128 v[158:161], v158 offset:3072
	ds_read_b128 v[174:177], v186
	ds_read_b128 v[178:181], v186 offset:1024
	ds_read_b128 v[182:185], v186 offset:2048
	ds_read_b128 v[186:189], v186 offset:3072
	s_add_u32 s46, s52, 0xb0000
	s_addc_u32 s47, s53, 0
	s_mov_b32 m0, s58
	v_lshl_add_u64 v[240:241], s[46:47], 0, v[134:135]
	ds_read_b128 v[200:203], v145 offset:32768
	ds_read_b128 v[208:211], v145 offset:33792
	ds_read_b128 v[212:215], v145 offset:34816
	ds_read_b128 v[216:219], v145 offset:35840
	ds_read_b128 v[220:223], v145 offset:36864
	ds_read_b128 v[224:227], v145 offset:37888
	ds_read_b128 v[228:231], v145 offset:38912
	ds_read_b128 v[232:235], v145 offset:39936
	global_load_lds_dwordx4 v[240:241], off
	v_lshl_add_u64 v[240:241], s[46:47], 0, v[132:133]
	s_mov_b32 m0, s59
	s_nop 0
	global_load_lds_dwordx4 v[240:241], off
	s_waitcnt vmcnt(8)
	s_waitcnt lgkmcnt(0)
	s_barrier
	s_setprio 1
	s_waitcnt lgkmcnt(0)
	v_mfma_f32_16x16x32_bf16 v[126:129], v[146:149], v[200:203], v[126:129]
	v_mfma_f32_16x16x32_bf16 v[122:125], v[154:157], v[200:203], v[122:125]
	v_mfma_f32_16x16x32_bf16 v[114:117], v[146:149], v[212:215], v[114:117]
	v_mfma_f32_16x16x32_bf16 v[106:109], v[154:157], v[212:215], v[106:109]
	v_mfma_f32_16x16x32_bf16 v[98:101], v[146:149], v[220:223], v[98:101]
	v_mfma_f32_16x16x32_bf16 v[90:93], v[154:157], v[220:223], v[90:93]
	v_mfma_f32_16x16x32_bf16 v[82:85], v[146:149], v[228:231], v[82:85]
	v_mfma_f32_16x16x32_bf16 v[74:77], v[154:157], v[228:231], v[74:77]
	v_mfma_f32_16x16x32_bf16 v[126:129], v[150:153], v[208:211], v[126:129]
	v_mfma_f32_16x16x32_bf16 v[122:125], v[158:161], v[208:211], v[122:125]
	v_mfma_f32_16x16x32_bf16 v[114:117], v[150:153], v[216:219], v[114:117]
	v_mfma_f32_16x16x32_bf16 v[106:109], v[158:161], v[216:219], v[106:109]
	v_mfma_f32_16x16x32_bf16 v[98:101], v[150:153], v[224:227], v[98:101]
	v_mfma_f32_16x16x32_bf16 v[90:93], v[158:161], v[224:227], v[90:93]
	v_mfma_f32_16x16x32_bf16 v[82:85], v[150:153], v[232:235], v[82:85]
	v_mfma_f32_16x16x32_bf16 v[74:77], v[158:161], v[232:235], v[74:77]
	s_setprio 0
	s_setprio 1
	v_mfma_f32_16x16x32_bf16 v[118:121], v[174:177], v[200:203], v[118:121]
	v_mfma_f32_16x16x32_bf16 v[110:113], v[182:185], v[200:203], v[110:113]
	v_mfma_f32_16x16x32_bf16 v[102:105], v[174:177], v[212:215], v[102:105]
	v_mfma_f32_16x16x32_bf16 v[94:97], v[182:185], v[212:215], v[94:97]
	v_mfma_f32_16x16x32_bf16 v[86:89], v[174:177], v[220:223], v[86:89]
	v_mfma_f32_16x16x32_bf16 v[78:81], v[182:185], v[220:223], v[78:81]
	v_mfma_f32_16x16x32_bf16 v[70:73], v[174:177], v[228:231], v[70:73]
	v_mfma_f32_16x16x32_bf16 v[66:69], v[182:185], v[228:231], v[66:69]
	v_mfma_f32_16x16x32_bf16 v[118:121], v[178:181], v[208:211], v[118:121]
	v_mfma_f32_16x16x32_bf16 v[110:113], v[186:189], v[208:211], v[110:113]
	v_mfma_f32_16x16x32_bf16 v[102:105], v[178:181], v[216:219], v[102:105]
	v_mfma_f32_16x16x32_bf16 v[94:97], v[186:189], v[216:219], v[94:97]
	v_mfma_f32_16x16x32_bf16 v[86:89], v[178:181], v[224:227], v[86:89]
	v_mfma_f32_16x16x32_bf16 v[78:81], v[186:189], v[224:227], v[78:81]
	v_mfma_f32_16x16x32_bf16 v[70:73], v[178:181], v[232:235], v[70:73]
	v_mfma_f32_16x16x32_bf16 v[66:69], v[186:189], v[232:235], v[66:69]
	s_setprio 0
	s_barrier
; #define PG8_STAGE(bufoff, gbase, voff) do { _Pragma("unroll") for (int _i = 0; _i < 2; ++_i) \
;         __builtin_amdgcn_global_load_lds((const unsigned*)((const char*)(gbase) + (voff)[_i]), (PG8_LAS unsigned*)(lds + (bufoff) + ldsw + _i * 8192), 16, 0, 0); } while (0)
; #define PG8_STAGEA(bufoff, gbase, voff) do { _Pragma("unroll") for (int _i = 0; _i < 2; ++_i) \
;         __builtin_amdgcn_global_load_lds((const unsigned*)((const char*)(gbase) + (voff)[_i]), (PG8_LAS unsigned*)(lds + (bufoff) + ldsw + _i * 8192), 16, 0, A_AUX); } while (0)
; #define PG8_LDA(dst, b, h) do { _Pragma("unroll") for (int m = 0; m < 4; ++m) _Pragma("unroll") for (int k = 0; k < 2; ++k) dst[m][k] = *(const PG8_LAS bf16x8*)(lds + PG8_SA(b, h) + aoff + m * 2048 + k * 1024); } while (0)
; #define PG8_WAIT_V(n) asm volatile("s_waitcnt vmcnt(" #n ")" ::: "memory")
; #define PG8_BAR __builtin_amdgcn_s_barrier()
;     ...
;         for (int t = 0; t < nt; t += 2) {
;             const bool last = (t == nt - 2);
;             const char* a1 = cA + (size_t)(t + 1) * kstep;
;             const char* a2 = last ? nA : cA + (size_t)(t + 2) * kstep; const char* b2 = last ? nB : cB + (size_t)(t + 2) * kstep;
;             const char* a3 = a2 + kstep; const char* b3 = b2 + kstep;
;             if (last && has_next) S.a_ready(nxt);
;             if constexpr (SP2) {
;             PG8_LDB(B0, 0, 0); PG8_LDB(B1, 0, 1); PG8_SCHED; PG8_LDA(At, 0, 0); PG8_STAGEA(PG8_SA(1, 1), a1 + hstep, voffA);
;             PG8_WAIT_V(8); PG8_WAIT_L(0); PG8_BAR; PG8_MMA(0, 0, At, B0); PG8_MMA(0, 1, At, B1); PG8_BAR; PG8_SCHED;
;             PG8_LDA(At, 0, 1); PG8_STAGE(PG8_SB(0, 0), b2, voffB); PG8_STAGE(PG8_SB(0, 1), b2 + hstep, voffB); PG8_STAGEA(PG8_SA(0, 0), a2, voffA);
;             PG8_WAIT_V(8); PG8_WAIT_L(0); PG8_BAR; PG8_MMA(1, 0, At, B0); PG8_MMA(1, 1, At, B1); PG8_BAR; PG8_SCHED;
;             PG8_LDB(B0, 1, 0); PG8_LDB(B1, 1, 1); PG8_SCHED; PG8_LDA(At, 1, 0); PG8_STAGEA(PG8_SA(0, 1), a2 + hstep, voffA);
;             PG8_WAIT_V(8); PG8_WAIT_L(0); PG8_BAR; PG8_MMA(0, 0, At, B0); PG8_MMA(0, 1, At, B1); PG8_BAR; PG8_SCHED;
;             PG8_LDA(At, 1, 1); PG8_STAGE(PG8_SB(1, 0), b3, voffB); PG8_STAGE(PG8_SB(1, 1), b3 + hstep, voffB); PG8_STAGEA(PG8_SA(1, 0), a3, voffA);
;             PG8_WAIT_V(8); PG8_WAIT_L(0); PG8_BAR; PG8_MMA(1, 0, At, B0); PG8_MMA(1, 1, At, B1); PG8_BAR; PG8_SCHED;
	s_add_i32 s46, s70, s55
	v_lshl_add_u64 v[140:141], v[140:141], 0, s[8:9]
	s_mov_b32 m0, s46
	ds_read_b128 v[200:203], v145 offset:49152
	ds_read_b128 v[208:211], v145 offset:50176
	ds_read_b128 v[212:215], v145 offset:51200
	ds_read_b128 v[216:219], v145 offset:52224
	ds_read_b128 v[220:223], v145 offset:53248
	ds_read_b128 v[224:227], v145 offset:54272
	ds_read_b128 v[228:231], v145 offset:55296
	ds_read_b128 v[232:235], v145 offset:56320
	global_load_lds_dwordx4 v[140:141], off
	s_add_i32 m0, s46, 0x2000
	s_add_u32 s46, s50, 0xb0080
	v_lshl_add_u64 v[140:141], v[190:191], 0, s[8:9]
	s_addc_u32 s47, s51, 0
	s_add_i32 s50, s71, s55
	global_load_lds_dwordx4 v[140:141], off
	v_lshl_add_u64 v[140:141], s[46:47], 0, v[0:1]
	s_mov_b32 m0, s50
	s_nop 0
	global_load_lds_dwordx4 v[140:141], off
	v_lshl_add_u64 v[140:141], s[46:47], 0, v[130:131]
	s_add_i32 m0, s50, 0x2000
	s_nop 0
	global_load_lds_dwordx4 v[140:141], off
	v_lshl_add_u64 v[140:141], v[236:237], 0, s[8:9]
	s_mov_b32 m0, s60
	s_nop 0
	global_load_lds_dwordx4 v[140:141], off
	v_lshl_add_u64 v[140:141], v[238:239], 0, s[8:9]
	s_mov_b32 m0, s61
	s_nop 0
	global_load_lds_dwordx4 v[140:141], off
	s_waitcnt vmcnt(8)
	s_waitcnt lgkmcnt(0)
	s_barrier
	s_setprio 1
	s_waitcnt lgkmcnt(0)
	v_mfma_f32_16x16x32_bf16 v[62:65], v[146:149], v[200:203], v[62:65]
	v_mfma_f32_16x16x32_bf16 v[58:61], v[154:157], v[200:203], v[58:61]
	v_mfma_f32_16x16x32_bf16 v[50:53], v[146:149], v[212:215], v[50:53]
	v_mfma_f32_16x16x32_bf16 v[42:45], v[154:157], v[212:215], v[42:45]
	v_mfma_f32_16x16x32_bf16 v[34:37], v[146:149], v[220:223], v[34:37]
	v_mfma_f32_16x16x32_bf16 v[26:29], v[154:157], v[220:223], v[26:29]
	v_mfma_f32_16x16x32_bf16 v[18:21], v[146:149], v[228:231], v[18:21]
	v_mfma_f32_16x16x32_bf16 v[10:13], v[154:157], v[228:231], v[10:13]
	v_mfma_f32_16x16x32_bf16 v[62:65], v[150:153], v[208:211], v[62:65]
	v_mfma_f32_16x16x32_bf16 v[58:61], v[158:161], v[208:211], v[58:61]
	v_mfma_f32_16x16x32_bf16 v[50:53], v[150:153], v[216:219], v[50:53]
	v_mfma_f32_16x16x32_bf16 v[42:45], v[158:161], v[216:219], v[42:45]
	v_mfma_f32_16x16x32_bf16 v[34:37], v[150:153], v[224:227], v[34:37]
	v_mfma_f32_16x16x32_bf16 v[26:29], v[158:161], v[224:227], v[26:29]
	v_mfma_f32_16x16x32_bf16 v[18:21], v[150:153], v[232:235], v[18:21]
	v_mfma_f32_16x16x32_bf16 v[10:13], v[158:161], v[232:235], v[10:13]
	s_setprio 0
	s_setprio 1
	v_mfma_f32_16x16x32_bf16 v[54:57], v[174:177], v[200:203], v[54:57]
	v_mfma_f32_16x16x32_bf16 v[46:49], v[182:185], v[200:203], v[46:49]
	v_mfma_f32_16x16x32_bf16 v[38:41], v[174:177], v[212:215], v[38:41]
	v_mfma_f32_16x16x32_bf16 v[30:33], v[182:185], v[212:215], v[30:33]
	s_add_i32 s73, s73, 2
	s_add_u32 s16, s16, 0x100
	s_addc_u32 s17, s17, 0
	s_mov_b64 s[46:47], s[48:49]
	s_add_u32 s48, s46, 0x100
	s_addc_u32 s49, s47, 0
	s_add_i32 s70, 0, 0x10000
	s_cmp_eq_u32 s73, 40
	s_cselect_b32 s53, s1, s49
	s_cselect_b32 s52, s0, s48
	s_cselect_b32 s51, s45, s17
	s_cselect_b32 s50, s44, s16
	s_add_i32 s71, 0, 0x14000
	v_mfma_f32_16x16x32_bf16 v[22:25], v[174:177], v[220:223], v[22:25]
	v_mfma_f32_16x16x32_bf16 v[14:17], v[182:185], v[220:223], v[14:17]
	v_mfma_f32_16x16x32_bf16 v[6:9], v[174:177], v[228:231], v[6:9]
	v_mfma_f32_16x16x32_bf16 v[2:5], v[182:185], v[228:231], v[2:5]
	v_mfma_f32_16x16x32_bf16 v[54:57], v[178:181], v[208:211], v[54:57]
	v_mfma_f32_16x16x32_bf16 v[46:49], v[186:189], v[208:211], v[46:49]
	v_mfma_f32_16x16x32_bf16 v[38:41], v[178:181], v[216:219], v[38:41]
	v_mfma_f32_16x16x32_bf16 v[30:33], v[186:189], v[216:219], v[30:33]
	v_mfma_f32_16x16x32_bf16 v[22:25], v[178:181], v[224:227], v[22:25]
	v_mfma_f32_16x16x32_bf16 v[14:17], v[186:189], v[224:227], v[14:17]
	v_mfma_f32_16x16x32_bf16 v[6:9], v[178:181], v[232:235], v[6:9]
	v_mfma_f32_16x16x32_bf16 v[2:5], v[186:189], v[232:235], v[2:5]
	s_setprio 0
	s_barrier
	s_cmp_gt_u32 s73, 41
.LBB0_656:
	v_add_u32_e32 v140, s70, v143
	ds_read_b128 v[146:149], v140
	ds_read_b128 v[150:153], v140 offset:1024
	ds_read_b128 v[154:157], v140 offset:2048
	ds_read_b128 v[158:161], v140 offset:3072
	v_add_u32_e32 v140, s71, v143
	ds_read_b128 v[174:177], v140
	ds_read_b128 v[178:181], v140 offset:1024
	ds_read_b128 v[182:185], v140 offset:2048
	ds_read_b128 v[186:189], v140 offset:3072
	v_lshl_add_u64 v[140:141], s[46:47], 0, v[136:137]
	s_add_i32 m0, s56, 0xc000
	ds_read_b128 v[200:203], v145
	ds_read_b128 v[208:211], v145 offset:1024
	ds_read_b128 v[212:215], v145 offset:2048
	ds_read_b128 v[216:219], v145 offset:3072
	ds_read_b128 v[220:223], v145 offset:4096
	ds_read_b128 v[224:227], v145 offset:5120
	ds_read_b128 v[228:231], v145 offset:6144
	ds_read_b128 v[232:235], v145 offset:7168
	global_load_lds_dwordx4 v[140:141], off
	v_lshl_add_u64 v[140:141], s[46:47], 0, v[138:139]
	s_add_i32 m0, s56, 0xe000
	s_nop 0
	global_load_lds_dwordx4 v[140:141], off
	s_waitcnt vmcnt(8)
	s_waitcnt lgkmcnt(0)
	s_barrier
; #define PG8_STAGE(bufoff, gbase, voff) do { _Pragma("unroll") for (int _i = 0; _i < 2; ++_i) \
;         __builtin_amdgcn_global_load_lds((const unsigned*)((const char*)(gbase) + (voff)[_i]), (PG8_LAS unsigned*)(lds + (bufoff) + ldsw + _i * 8192), 16, 0, 0); } while (0)
; #define PG8_STAGEA(bufoff, gbase, voff) do { _Pragma("unroll") for (int _i = 0; _i < 2; ++_i) \
;         __builtin_amdgcn_global_load_lds((const unsigned*)((const char*)(gbase) + (voff)[_i]), (PG8_LAS unsigned*)(lds + (bufoff) + ldsw + _i * 8192), 16, 0, A_AUX); } while (0)
; #define PG8_LDA(dst, b, h) do { _Pragma("unroll") for (int m = 0; m < 4; ++m) _Pragma("unroll") for (int k = 0; k < 2; ++k) dst[m][k] = *(const PG8_LAS bf16x8*)(lds + PG8_SA(b, h) + aoff + m * 2048 + k * 1024); } while (0)
; #define PG8_LDB(dst, b, h) do { _Pragma("unroll") for (int n = 0; n < 2; ++n) _Pragma("unroll") for (int k = 0; k < 2; ++k) dst[n][k] = *(const PG8_LAS bf16x8*)(lds + PG8_SB(b, h) + boff + n * 2048 + k * 1024); } while (0)
; #define PG8_MMA(ai, bj, At, Bt) do { __builtin_amdgcn_s_setprio(1); _Pragma("unroll") for (int m = 0; m < 4; ++m) _Pragma("unroll") for (int n = 0; n < 2; ++n) _Pragma("unroll") for (int k = 0; k < 2; ++k) \
;         acc[ai][bj][m][n] = __builtin_amdgcn_mfma_f32_16x16x32_bf16(Bt[n][k], At[m][k], acc[ai][bj][m][n], 0, 0, 0); __builtin_amdgcn_s_setprio(0); } while (0)
; #define PG8_WAIT_V(n) asm volatile("s_waitcnt vmcnt(" #n ")" ::: "memory")
; #define PG8_WAIT_L(n) asm volatile("s_waitcnt lgkmcnt(" #n ")" ::: "memory")
; #define PG8_BAR __builtin_amdgcn_s_barrier()
; #define PG8_SCHED __builtin_amdgcn_sched_barrier(0)
;     ...
;             PG8_LDB(B0, 0, 0); PG8_LDB(B1, 0, 1); PG8_SCHED; PG8_LDA(At, 0, 0); PG8_STAGEA(PG8_SA(1, 1), a1 + hstep, voffA);
;             PG8_WAIT_V(8); PG8_WAIT_L(0); PG8_BAR; PG8_MMA(0, 0, At, B0); PG8_MMA(0, 1, At, B1); PG8_BAR; PG8_SCHED;
;             PG8_LDA(At, 0, 1); PG8_STAGE(PG8_SB(0, 0), b2, voffB); PG8_STAGE(PG8_SB(0, 1), b2 + hstep, voffB); PG8_STAGEA(PG8_SA(0, 0), a2, voffA);
;             PG8_WAIT_V(8); PG8_WAIT_L(0); PG8_BAR; PG8_MMA(1, 0, At, B0); PG8_MMA(1, 1, At, B1); PG8_BAR; PG8_SCHED;
;             PG8_LDB(B0, 1, 0); PG8_LDB(B1, 1, 1); PG8_SCHED; PG8_LDA(At, 1, 0); PG8_STAGEA(PG8_SA(0, 1), a2 + hstep, voffA);
;             PG8_WAIT_V(8); PG8_WAIT_L(0); PG8_BAR; PG8_MMA(0, 0, At, B0); PG8_MMA(0, 1, At, B1); PG8_BAR; PG8_SCHED;
	s_setprio 1
	s_waitcnt lgkmcnt(0)
	v_mfma_f32_16x16x32_bf16 v[126:129], v[146:149], v[200:203], v[126:129]
	v_mfma_f32_16x16x32_bf16 v[122:125], v[154:157], v[200:203], v[122:125]
	v_mfma_f32_16x16x32_bf16 v[114:117], v[146:149], v[212:215], v[114:117]
	v_mfma_f32_16x16x32_bf16 v[106:109], v[154:157], v[212:215], v[106:109]
	v_mfma_f32_16x16x32_bf16 v[98:101], v[146:149], v[220:223], v[98:101]
	v_mfma_f32_16x16x32_bf16 v[90:93], v[154:157], v[220:223], v[90:93]
	v_mfma_f32_16x16x32_bf16 v[82:85], v[146:149], v[228:231], v[82:85]
	v_mfma_f32_16x16x32_bf16 v[74:77], v[154:157], v[228:231], v[74:77]
	v_mfma_f32_16x16x32_bf16 v[126:129], v[150:153], v[208:211], v[126:129]
	v_mfma_f32_16x16x32_bf16 v[122:125], v[158:161], v[208:211], v[122:125]
	v_mfma_f32_16x16x32_bf16 v[114:117], v[150:153], v[216:219], v[114:117]
	v_mfma_f32_16x16x32_bf16 v[106:109], v[158:161], v[216:219], v[106:109]
	v_mfma_f32_16x16x32_bf16 v[98:101], v[150:153], v[224:227], v[98:101]
	v_mfma_f32_16x16x32_bf16 v[90:93], v[158:161], v[224:227], v[90:93]
	v_mfma_f32_16x16x32_bf16 v[82:85], v[150:153], v[232:235], v[82:85]
	v_mfma_f32_16x16x32_bf16 v[74:77], v[158:161], v[232:235], v[74:77]
	s_setprio 0
	s_setprio 1
	v_mfma_f32_16x16x32_bf16 v[118:121], v[174:177], v[200:203], v[118:121]
	v_mfma_f32_16x16x32_bf16 v[110:113], v[182:185], v[200:203], v[110:113]
	v_mfma_f32_16x16x32_bf16 v[102:105], v[174:177], v[212:215], v[102:105]
	v_mfma_f32_16x16x32_bf16 v[94:97], v[182:185], v[212:215], v[94:97]
	v_mfma_f32_16x16x32_bf16 v[86:89], v[174:177], v[220:223], v[86:89]
	v_mfma_f32_16x16x32_bf16 v[78:81], v[182:185], v[220:223], v[78:81]
	v_mfma_f32_16x16x32_bf16 v[70:73], v[174:177], v[228:231], v[70:73]
	v_mfma_f32_16x16x32_bf16 v[66:69], v[182:185], v[228:231], v[66:69]
	v_mfma_f32_16x16x32_bf16 v[118:121], v[178:181], v[208:211], v[118:121]
	v_mfma_f32_16x16x32_bf16 v[110:113], v[186:189], v[208:211], v[110:113]
	v_mfma_f32_16x16x32_bf16 v[102:105], v[178:181], v[216:219], v[102:105]
	v_mfma_f32_16x16x32_bf16 v[94:97], v[186:189], v[216:219], v[94:97]
	v_mfma_f32_16x16x32_bf16 v[86:89], v[178:181], v[224:227], v[86:89]
	v_mfma_f32_16x16x32_bf16 v[78:81], v[186:189], v[224:227], v[78:81]
	v_mfma_f32_16x16x32_bf16 v[70:73], v[178:181], v[232:235], v[70:73]
	v_mfma_f32_16x16x32_bf16 v[66:69], v[186:189], v[232:235], v[66:69]
	s_setprio 0
	s_barrier
	s_add_i32 s46, s70, s55
	v_lshl_add_u64 v[140:141], s[50:51], 0, v[0:1]
	s_mov_b32 m0, s46
	ds_read_b128 v[200:203], v145 offset:16384
	ds_read_b128 v[208:211], v145 offset:17408
	ds_read_b128 v[212:215], v145 offset:18432
	ds_read_b128 v[216:219], v145 offset:19456
	ds_read_b128 v[220:223], v145 offset:20480
	ds_read_b128 v[224:227], v145 offset:21504
	ds_read_b128 v[228:231], v145 offset:22528
	ds_read_b128 v[232:235], v145 offset:23552
	global_load_lds_dwordx4 v[140:141], off
	s_add_i32 m0, s46, 0x2000
	s_add_u32 s46, s50, 0xb0000
	v_lshl_add_u64 v[190:191], s[50:51], 0, v[130:131]
	s_addc_u32 s47, s51, 0
	s_add_i32 s70, s71, s55
	global_load_lds_dwordx4 v[190:191], off
	v_lshl_add_u64 v[236:237], s[46:47], 0, v[0:1]
	s_mov_b32 m0, s70
	v_lshl_add_u64 v[238:239], s[52:53], 0, v[132:133]
	global_load_lds_dwordx4 v[236:237], off
	v_lshl_add_u64 v[236:237], s[46:47], 0, v[130:131]
	s_add_i32 m0, s70, 0x2000
	s_nop 0
	global_load_lds_dwordx4 v[236:237], off
	v_lshl_add_u64 v[236:237], s[52:53], 0, v[134:135]
	s_mov_b32 m0, s56
	s_nop 0
	global_load_lds_dwordx4 v[236:237], off
	s_mov_b32 m0, s57
	s_nop 0
	global_load_lds_dwordx4 v[238:239], off
	s_waitcnt vmcnt(8)
	s_waitcnt lgkmcnt(0)
	s_barrier
	s_setprio 1
	s_waitcnt lgkmcnt(0)
	v_mfma_f32_16x16x32_bf16 v[62:65], v[146:149], v[200:203], v[62:65]
	v_mfma_f32_16x16x32_bf16 v[58:61], v[154:157], v[200:203], v[58:61]
	v_mfma_f32_16x16x32_bf16 v[50:53], v[146:149], v[212:215], v[50:53]
	v_mfma_f32_16x16x32_bf16 v[42:45], v[154:157], v[212:215], v[42:45]
	v_mfma_f32_16x16x32_bf16 v[34:37], v[146:149], v[220:223], v[34:37]
	v_mfma_f32_16x16x32_bf16 v[26:29], v[154:157], v[220:223], v[26:29]
	v_mfma_f32_16x16x32_bf16 v[18:21], v[146:149], v[228:231], v[18:21]
	v_mfma_f32_16x16x32_bf16 v[10:13], v[154:157], v[228:231], v[10:13]
	v_mfma_f32_16x16x32_bf16 v[62:65], v[150:153], v[208:211], v[62:65]
	v_mfma_f32_16x16x32_bf16 v[58:61], v[158:161], v[208:211], v[58:61]
	v_mfma_f32_16x16x32_bf16 v[50:53], v[150:153], v[216:219], v[50:53]
	v_mfma_f32_16x16x32_bf16 v[42:45], v[158:161], v[216:219], v[42:45]
	v_mfma_f32_16x16x32_bf16 v[34:37], v[150:153], v[224:227], v[34:37]
	v_mfma_f32_16x16x32_bf16 v[26:29], v[158:161], v[224:227], v[26:29]
	v_mfma_f32_16x16x32_bf16 v[18:21], v[150:153], v[232:235], v[18:21]
	v_mfma_f32_16x16x32_bf16 v[10:13], v[158:161], v[232:235], v[10:13]
	s_setprio 0
	s_setprio 1
	v_mfma_f32_16x16x32_bf16 v[54:57], v[174:177], v[200:203], v[54:57]
	v_mfma_f32_16x16x32_bf16 v[46:49], v[182:185], v[200:203], v[46:49]
	v_mfma_f32_16x16x32_bf16 v[38:41], v[174:177], v[212:215], v[38:41]
	v_mfma_f32_16x16x32_bf16 v[30:33], v[182:185], v[212:215], v[30:33]
	v_mfma_f32_16x16x32_bf16 v[22:25], v[174:177], v[220:223], v[22:25]
	v_mfma_f32_16x16x32_bf16 v[14:17], v[182:185], v[220:223], v[14:17]
	v_mfma_f32_16x16x32_bf16 v[6:9], v[174:177], v[228:231], v[6:9]
	v_mfma_f32_16x16x32_bf16 v[2:5], v[182:185], v[228:231], v[2:5]
	v_mfma_f32_16x16x32_bf16 v[54:57], v[178:181], v[208:211], v[54:57]
	v_mfma_f32_16x16x32_bf16 v[46:49], v[186:189], v[208:211], v[46:49]
	v_mfma_f32_16x16x32_bf16 v[38:41], v[178:181], v[216:219], v[38:41]
	v_mfma_f32_16x16x32_bf16 v[30:33], v[186:189], v[216:219], v[30:33]
	v_mfma_f32_16x16x32_bf16 v[22:25], v[178:181], v[224:227], v[22:25]
	v_mfma_f32_16x16x32_bf16 v[14:17], v[186:189], v[224:227], v[14:17]
	v_mfma_f32_16x16x32_bf16 v[6:9], v[178:181], v[232:235], v[6:9]
	v_mfma_f32_16x16x32_bf16 v[2:5], v[186:189], v[232:235], v[2:5]
	s_setprio 0
	s_barrier
; #define PG8_STAGEA(bufoff, gbase, voff) do { _Pragma("unroll") for (int _i = 0; _i < 2; ++_i) \
;         __builtin_amdgcn_global_load_lds((const unsigned*)((const char*)(gbase) + (voff)[_i]), (PG8_LAS unsigned*)(lds + (bufoff) + ldsw + _i * 8192), 16, 0, A_AUX); } while (0)
; #define PG8_LDA(dst, b, h) do { _Pragma("unroll") for (int m = 0; m < 4; ++m) _Pragma("unroll") for (int k = 0; k < 2; ++k) dst[m][k] = *(const PG8_LAS bf16x8*)(lds + PG8_SA(b, h) + aoff + m * 2048 + k * 1024); } while (0)
; #define PG8_LDB(dst, b, h) do { _Pragma("unroll") for (int n = 0; n < 2; ++n) _Pragma("unroll") for (int k = 0; k < 2; ++k) dst[n][k] = *(const PG8_LAS bf16x8*)(lds + PG8_SB(b, h) + boff + n * 2048 + k * 1024); } while (0)
; #define PG8_MMA(ai, bj, At, Bt) do { __builtin_amdgcn_s_setprio(1); _Pragma("unroll") for (int m = 0; m < 4; ++m) _Pragma("unroll") for (int n = 0; n < 2; ++n) _Pragma("unroll") for (int k = 0; k < 2; ++k) \
;         acc[ai][bj][m][n] = __builtin_amdgcn_mfma_f32_16x16x32_bf16(Bt[n][k], At[m][k], acc[ai][bj][m][n], 0, 0, 0); __builtin_amdgcn_s_setprio(0); } while (0)
; #define PG8_WAIT_V(n) asm volatile("s_waitcnt vmcnt(" #n ")" ::: "memory")
; #define PG8_WAIT_L(n) asm volatile("s_waitcnt lgkmcnt(" #n ")" ::: "memory")
; #define PG8_BAR __builtin_amdgcn_s_barrier()
; #define PG8_SCHED __builtin_amdgcn_sched_barrier(0)
;     ...
;             PG8_LDB(B0, 1, 0); PG8_LDB(B1, 1, 1); PG8_SCHED; PG8_LDA(At, 1, 0); PG8_STAGEA(PG8_SA(0, 1), a2 + hstep, voffA);
;             PG8_WAIT_V(8); PG8_WAIT_L(0); PG8_BAR; PG8_MMA(0, 0, At, B0); PG8_MMA(0, 1, At, B1); PG8_BAR; PG8_SCHED;
	s_add_i32 s70, 0, 0x18000
	s_add_i32 s71, 0, 0x1c000
	v_add_u32_e32 v158, s70, v143
	v_add_u32_e32 v186, s71, v143
	ds_read_b128 v[146:149], v158
	ds_read_b128 v[150:153], v158 offset:1024
	ds_read_b128 v[154:157], v158 offset:2048
	ds_read_b128 v[158:161], v158 offset:3072
	ds_read_b128 v[174:177], v186
	ds_read_b128 v[178:181], v186 offset:1024
	ds_read_b128 v[182:185], v186 offset:2048
	ds_read_b128 v[186:189], v186 offset:3072
	s_add_u32 s46, s52, 0xb0000
	s_addc_u32 s47, s53, 0
	s_mov_b32 m0, s58
	v_lshl_add_u64 v[240:241], s[46:47], 0, v[134:135]
	ds_read_b128 v[200:203], v145 offset:32768
	ds_read_b128 v[208:211], v145 offset:33792
	ds_read_b128 v[212:215], v145 offset:34816
	ds_read_b128 v[216:219], v145 offset:35840
	ds_read_b128 v[220:223], v145 offset:36864
	ds_read_b128 v[224:227], v145 offset:37888
	ds_read_b128 v[228:231], v145 offset:38912
	ds_read_b128 v[232:235], v145 offset:39936
	global_load_lds_dwordx4 v[240:241], off
	v_lshl_add_u64 v[240:241], s[46:47], 0, v[132:133]
	s_mov_b32 m0, s59
	s_nop 0
	global_load_lds_dwordx4 v[240:241], off
	s_waitcnt vmcnt(8)
	s_waitcnt lgkmcnt(0)
	s_barrier
	s_setprio 1
	s_waitcnt lgkmcnt(0)
	v_mfma_f32_16x16x32_bf16 v[126:129], v[146:149], v[200:203], v[126:129]
	v_mfma_f32_16x16x32_bf16 v[122:125], v[154:157], v[200:203], v[122:125]
	v_mfma_f32_16x16x32_bf16 v[114:117], v[146:149], v[212:215], v[114:117]
	v_mfma_f32_16x16x32_bf16 v[106:109], v[154:157], v[212:215], v[106:109]
	v_mfma_f32_16x16x32_bf16 v[98:101], v[146:149], v[220:223], v[98:101]
	v_mfma_f32_16x16x32_bf16 v[90:93], v[154:157], v[220:223], v[90:93]
	v_mfma_f32_16x16x32_bf16 v[82:85], v[146:149], v[228:231], v[82:85]
	v_mfma_f32_16x16x32_bf16 v[74:77], v[154:157], v[228:231], v[74:77]
	v_mfma_f32_16x16x32_bf16 v[126:129], v[150:153], v[208:211], v[126:129]
	v_mfma_f32_16x16x32_bf16 v[122:125], v[158:161], v[208:211], v[122:125]
	v_mfma_f32_16x16x32_bf16 v[114:117], v[150:153], v[216:219], v[114:117]
	v_mfma_f32_16x16x32_bf16 v[106:109], v[158:161], v[216:219], v[106:109]
	v_mfma_f32_16x16x32_bf16 v[98:101], v[150:153], v[224:227], v[98:101]
	v_mfma_f32_16x16x32_bf16 v[90:93], v[158:161], v[224:227], v[90:93]
	v_mfma_f32_16x16x32_bf16 v[82:85], v[150:153], v[232:235], v[82:85]
	v_mfma_f32_16x16x32_bf16 v[74:77], v[158:161], v[232:235], v[74:77]
	s_setprio 0
	s_setprio 1
	v_mfma_f32_16x16x32_bf16 v[118:121], v[174:177], v[200:203], v[118:121]
	v_mfma_f32_16x16x32_bf16 v[110:113], v[182:185], v[200:203], v[110:113]
	v_mfma_f32_16x16x32_bf16 v[102:105], v[174:177], v[212:215], v[102:105]
	v_mfma_f32_16x16x32_bf16 v[94:97], v[182:185], v[212:215], v[94:97]
	v_mfma_f32_16x16x32_bf16 v[86:89], v[174:177], v[220:223], v[86:89]
	v_mfma_f32_16x16x32_bf16 v[78:81], v[182:185], v[220:223], v[78:81]
	v_mfma_f32_16x16x32_bf16 v[70:73], v[174:177], v[228:231], v[70:73]
	v_mfma_f32_16x16x32_bf16 v[66:69], v[182:185], v[228:231], v[66:69]
	v_mfma_f32_16x16x32_bf16 v[118:121], v[178:181], v[208:211], v[118:121]
	v_mfma_f32_16x16x32_bf16 v[110:113], v[186:189], v[208:211], v[110:113]
	v_mfma_f32_16x16x32_bf16 v[102:105], v[178:181], v[216:219], v[102:105]
	v_mfma_f32_16x16x32_bf16 v[94:97], v[186:189], v[216:219], v[94:97]
	v_mfma_f32_16x16x32_bf16 v[86:89], v[178:181], v[224:227], v[86:89]
	v_mfma_f32_16x16x32_bf16 v[78:81], v[186:189], v[224:227], v[78:81]
	v_mfma_f32_16x16x32_bf16 v[70:73], v[178:181], v[232:235], v[70:73]
	v_mfma_f32_16x16x32_bf16 v[66:69], v[186:189], v[232:235], v[66:69]
	s_setprio 0
	s_barrier
; #define PG8_STAGE(bufoff, gbase, voff) do { _Pragma("unroll") for (int _i = 0; _i < 2; ++_i) \
;         __builtin_amdgcn_global_load_lds((const unsigned*)((const char*)(gbase) + (voff)[_i]), (PG8_LAS unsigned*)(lds + (bufoff) + ldsw + _i * 8192), 16, 0, 0); } while (0)
; #define PG8_STAGEA(bufoff, gbase, voff) do { _Pragma("unroll") for (int _i = 0; _i < 2; ++_i) \
;         __builtin_amdgcn_global_load_lds((const unsigned*)((const char*)(gbase) + (voff)[_i]), (PG8_LAS unsigned*)(lds + (bufoff) + ldsw + _i * 8192), 16, 0, A_AUX); } while (0)
; #define PG8_LDA(dst, b, h) do { _Pragma("unroll") for (int m = 0; m < 4; ++m) _Pragma("unroll") for (int k = 0; k < 2; ++k) dst[m][k] = *(const PG8_LAS bf16x8*)(lds + PG8_SA(b, h) + aoff + m * 2048 + k * 1024); } while (0)
; #define PG8_WAIT_V(n) asm volatile("s_waitcnt vmcnt(" #n ")" ::: "memory")
; #define PG8_BAR __builtin_amdgcn_s_barrier()
;     ...
;         for (int t = 0; t < nt; t += 2) {
;             const bool last = (t == nt - 2);
;             const char* a1 = cA + (size_t)(t + 1) * kstep;
;             const char* a2 = last ? nA : cA + (size_t)(t + 2) * kstep; const char* b2 = last ? nB : cB + (size_t)(t + 2) * kstep;
;             const char* a3 = a2 + kstep; const char* b3 = b2 + kstep;
;             if (last && has_next) S.a_ready(nxt);
;             if constexpr (SP2) {
;             PG8_LDB(B0, 0, 0); PG8_LDB(B1, 0, 1); PG8_SCHED; PG8_LDA(At, 0, 0); PG8_STAGEA(PG8_SA(1, 1), a1 + hstep, voffA);
;             PG8_WAIT_V(8); PG8_WAIT_L(0); PG8_BAR; PG8_MMA(0, 0, At, B0); PG8_MMA(0, 1, At, B1); PG8_BAR; PG8_SCHED;
;             PG8_LDA(At, 0, 1); PG8_STAGE(PG8_SB(0, 0), b2, voffB); PG8_STAGE(PG8_SB(0, 1), b2 + hstep, voffB); PG8_STAGEA(PG8_SA(0, 0), a2, voffA);
;             PG8_WAIT_V(8); PG8_WAIT_L(0); PG8_BAR; PG8_MMA(1, 0, At, B0); PG8_MMA(1, 1, At, B1); PG8_BAR; PG8_SCHED;
;             PG8_LDB(B0, 1, 0); PG8_LDB(B1, 1, 1); PG8_SCHED; PG8_LDA(At, 1, 0); PG8_STAGEA(PG8_SA(0, 1), a2 + hstep, voffA);
;             PG8_WAIT_V(8); PG8_WAIT_L(0); PG8_BAR; PG8_MMA(0, 0, At, B0); PG8_MMA(0, 1, At, B1); PG8_BAR; PG8_SCHED;
;             PG8_LDA(At, 1, 1); PG8_STAGE(PG8_SB(1, 0), b3, voffB); PG8_STAGE(PG8_SB(1, 1), b3 + hstep, voffB); PG8_STAGEA(PG8_SA(1, 0), a3, voffA);
;             PG8_WAIT_V(8); PG8_WAIT_L(0); PG8_BAR; PG8_MMA(1, 0, At, B0); PG8_MMA(1, 1, At, B1); PG8_BAR; PG8_SCHED;
	s_add_i32 s46, s70, s55
	v_lshl_add_u64 v[140:141], v[140:141], 0, s[8:9]
	s_mov_b32 m0, s46
	ds_read_b128 v[200:203], v145 offset:49152
	ds_read_b128 v[208:211], v145 offset:50176
	ds_read_b128 v[212:215], v145 offset:51200
	ds_read_b128 v[216:219], v145 offset:52224
	ds_read_b128 v[220:223], v145 offset:53248
	ds_read_b128 v[224:227], v145 offset:54272
	ds_read_b128 v[228:231], v145 offset:55296
	ds_read_b128 v[232:235], v145 offset:56320
	global_load_lds_dwordx4 v[140:141], off
	s_add_i32 m0, s46, 0x2000
	s_add_u32 s46, s50, 0xb0080
	v_lshl_add_u64 v[140:141], v[190:191], 0, s[8:9]
	s_addc_u32 s47, s51, 0
	s_add_i32 s50, s71, s55
	global_load_lds_dwordx4 v[140:141], off
	v_lshl_add_u64 v[140:141], s[46:47], 0, v[0:1]
	s_mov_b32 m0, s50
	s_nop 0
	global_load_lds_dwordx4 v[140:141], off
	v_lshl_add_u64 v[140:141], s[46:47], 0, v[130:131]
	s_add_i32 m0, s50, 0x2000
	s_nop 0
	global_load_lds_dwordx4 v[140:141], off
	v_lshl_add_u64 v[140:141], v[236:237], 0, s[8:9]
	s_mov_b32 m0, s60
	s_nop 0
	global_load_lds_dwordx4 v[140:141], off
	v_lshl_add_u64 v[140:141], v[238:239], 0, s[8:9]
	s_mov_b32 m0, s61
	s_nop 0
	global_load_lds_dwordx4 v[140:141], off
	s_waitcnt vmcnt(8)
	s_waitcnt lgkmcnt(0)
	s_barrier
	s_setprio 1
	s_waitcnt lgkmcnt(0)
	v_mfma_f32_16x16x32_bf16 v[62:65], v[146:149], v[200:203], v[62:65]
	v_mfma_f32_16x16x32_bf16 v[58:61], v[154:157], v[200:203], v[58:61]
	v_mfma_f32_16x16x32_bf16 v[50:53], v[146:149], v[212:215], v[50:53]
	v_mfma_f32_16x16x32_bf16 v[42:45], v[154:157], v[212:215], v[42:45]
	v_mfma_f32_16x16x32_bf16 v[34:37], v[146:149], v[220:223], v[34:37]
	v_mfma_f32_16x16x32_bf16 v[26:29], v[154:157], v[220:223], v[26:29]
	v_mfma_f32_16x16x32_bf16 v[18:21], v[146:149], v[228:231], v[18:21]
	v_mfma_f32_16x16x32_bf16 v[10:13], v[154:157], v[228:231], v[10:13]
	v_mfma_f32_16x16x32_bf16 v[62:65], v[150:153], v[208:211], v[62:65]
	v_mfma_f32_16x16x32_bf16 v[58:61], v[158:161], v[208:211], v[58:61]
	v_mfma_f32_16x16x32_bf16 v[50:53], v[150:153], v[216:219], v[50:53]
	v_mfma_f32_16x16x32_bf16 v[42:45], v[158:161], v[216:219], v[42:45]
	v_mfma_f32_16x16x32_bf16 v[34:37], v[150:153], v[224:227], v[34:37]
	v_mfma_f32_16x16x32_bf16 v[26:29], v[158:161], v[224:227], v[26:29]
	v_mfma_f32_16x16x32_bf16 v[18:21], v[150:153], v[232:235], v[18:21]
	v_mfma_f32_16x16x32_bf16 v[10:13], v[158:161], v[232:235], v[10:13]
	s_setprio 0
	s_setprio 1
	v_mfma_f32_16x16x32_bf16 v[54:57], v[174:177], v[200:203], v[54:57]
	v_mfma_f32_16x16x32_bf16 v[46:49], v[182:185], v[200:203], v[46:49]
	v_mfma_f32_16x16x32_bf16 v[38:41], v[174:177], v[212:215], v[38:41]
	v_mfma_f32_16x16x32_bf16 v[30:33], v[182:185], v[212:215], v[30:33]
	s_add_i32 s73, s73, 2
	s_add_u32 s16, s16, 0x100
	s_addc_u32 s17, s17, 0
	s_mov_b64 s[46:47], s[48:49]
	s_add_u32 s48, s46, 0x100
	s_addc_u32 s49, s47, 0
	s_add_i32 s70, 0, 0x10000
	s_cmp_eq_u32 s73, 40
	s_cselect_b32 s53, s1, s49
	s_cselect_b32 s52, s0, s48
	s_cselect_b32 s51, s45, s17
	s_cselect_b32 s50, s44, s16
	s_add_i32 s71, 0, 0x14000
	v_mfma_f32_16x16x32_bf16 v[22:25], v[174:177], v[220:223], v[22:25]
	v_mfma_f32_16x16x32_bf16 v[14:17], v[182:185], v[220:223], v[14:17]
	v_mfma_f32_16x16x32_bf16 v[6:9], v[174:177], v[228:231], v[6:9]
	v_mfma_f32_16x16x32_bf16 v[2:5], v[182:185], v[228:231], v[2:5]
	v_mfma_f32_16x16x32_bf16 v[54:57], v[178:181], v[208:211], v[54:57]
	v_mfma_f32_16x16x32_bf16 v[46:49], v[186:189], v[208:211], v[46:49]
	v_mfma_f32_16x16x32_bf16 v[38:41], v[178:181], v[216:219], v[38:41]
	v_mfma_f32_16x16x32_bf16 v[30:33], v[186:189], v[216:219], v[30:33]
	v_mfma_f32_16x16x32_bf16 v[22:25], v[178:181], v[224:227], v[22:25]
	v_mfma_f32_16x16x32_bf16 v[14:17], v[186:189], v[224:227], v[14:17]
	v_mfma_f32_16x16x32_bf16 v[6:9], v[178:181], v[232:235], v[6:9]
	v_mfma_f32_16x16x32_bf16 v[2:5], v[186:189], v[232:235], v[2:5]
	s_setprio 0
	s_barrier
	s_cmp_gt_u32 s73, 41
	s_cbranch_scc0 .LBB0_656
	s_and_b64 vcc, exec, s[42:43]
	s_cbranch_vccz .LBB0_659
	s_barrier
